# GEMM K-loops: LDS-DMA loads use saddr form (SGPR base + 32-bit VGPR offset); the 16 per-iteration v_lshl_add_u64 address adds removed from the load sections
# speedup vs baseline: 1.0105x; 1.0058x over previous
.LBB0_197:
	ds_read_b128 v[144:147], v151
	ds_read_b128 v[154:157], v151 offset:1024
	ds_read_b128 v[158:161], v151 offset:2048
	ds_read_b128 v[162:165], v151 offset:3072
	s_add_u32 s18, s16, 0xfff80080
	s_addc_u32 s19, s17, -1
	s_cmp_eq_u32 s78, 28
	s_cselect_b32 s21, s5, s19
	s_cselect_b32 s20, s9, s18
	s_cselect_b32 s19, s7, s77
	s_cselect_b32 s18, s15, s76
	s_add_i32 m0, s24, 0xc000
	ds_read_b128 v[166:169], v152
	ds_read_b128 v[170:173], v152 offset:1024
	ds_read_b128 v[174:177], v152 offset:2048
	ds_read_b128 v[178:181], v152 offset:3072
	ds_read_b128 v[182:185], v152 offset:4096
	ds_read_b128 v[186:189], v152 offset:5120
	ds_read_b128 v[190:193], v152 offset:6144
	ds_read_b128 v[194:197], v152 offset:7168
	global_load_lds_dwordx4 v136, s[16:17]
	s_add_i32 m0, s24, 0xe000
	s_nop 0
	global_load_lds_dwordx4 v138, s[16:17]
	s_waitcnt lgkmcnt(8)
	s_barrier
	s_waitcnt lgkmcnt(0)
	v_mfma_f32_16x16x32_f16 v[124:127], v[144:147], v[166:169], v[124:127]
	v_mfma_f32_16x16x32_f16 v[120:123], v[158:161], v[166:169], v[120:123]
	v_mfma_f32_16x16x32_f16 v[108:111], v[144:147], v[174:177], v[108:111]
	v_mfma_f32_16x16x32_f16 v[104:107], v[158:161], v[174:177], v[104:107]
	v_mfma_f32_16x16x32_f16 v[92:95], v[144:147], v[182:185], v[92:95]
	v_mfma_f32_16x16x32_f16 v[88:91], v[158:161], v[182:185], v[88:91]
	v_mfma_f32_16x16x32_f16 v[76:79], v[144:147], v[190:193], v[76:79]
	v_mfma_f32_16x16x32_f16 v[72:75], v[158:161], v[190:193], v[72:75]
	v_mfma_f32_16x16x32_f16 v[124:127], v[154:157], v[170:173], v[124:127]
	v_mfma_f32_16x16x32_f16 v[120:123], v[162:165], v[170:173], v[120:123]
	v_mfma_f32_16x16x32_f16 v[108:111], v[154:157], v[178:181], v[108:111]
	v_mfma_f32_16x16x32_f16 v[104:107], v[162:165], v[178:181], v[104:107]
	v_mfma_f32_16x16x32_f16 v[92:95], v[154:157], v[186:189], v[92:95]
	v_mfma_f32_16x16x32_f16 v[88:91], v[162:165], v[186:189], v[88:91]
	v_mfma_f32_16x16x32_f16 v[76:79], v[154:157], v[194:197], v[76:79]
	v_mfma_f32_16x16x32_f16 v[72:75], v[162:165], v[194:197], v[72:75]
	s_barrier
	s_add_i32 s79, s68, s23
	s_add_u32 s72, s18, s0
	s_addc_u32 s73, s19, s1
	s_mov_b32 m0, s79
	ds_read_b128 v[198:201], v153
	ds_read_b128 v[202:205], v153 offset:1024
	ds_read_b128 v[206:209], v153 offset:2048
	ds_read_b128 v[210:213], v153 offset:3072
	global_load_lds_dwordx4 v130, s[18:19]
	s_add_i32 m0, s79, 0x2000
	s_nop 0
	global_load_lds_dwordx4 v134, s[18:19]
	s_barrier
	s_waitcnt lgkmcnt(0)
	v_mfma_f32_16x16x32_f16 v[116:119], v[198:201], v[166:169], v[116:119]
	v_mfma_f32_16x16x32_f16 v[112:115], v[206:209], v[166:169], v[112:115]
	v_mfma_f32_16x16x32_f16 v[100:103], v[198:201], v[174:177], v[100:103]
	v_mfma_f32_16x16x32_f16 v[96:99], v[206:209], v[174:177], v[96:99]
	v_mfma_f32_16x16x32_f16 v[84:87], v[198:201], v[182:185], v[84:87]
	v_mfma_f32_16x16x32_f16 v[80:83], v[206:209], v[182:185], v[80:83]
	v_mfma_f32_16x16x32_f16 v[68:71], v[198:201], v[190:193], v[68:71]
	v_mfma_f32_16x16x32_f16 v[64:67], v[206:209], v[190:193], v[64:67]
	v_mfma_f32_16x16x32_f16 v[116:119], v[202:205], v[170:173], v[116:119]
	v_mfma_f32_16x16x32_f16 v[112:115], v[210:213], v[170:173], v[112:115]
	v_mfma_f32_16x16x32_f16 v[100:103], v[202:205], v[178:181], v[100:103]
	v_mfma_f32_16x16x32_f16 v[96:99], v[210:213], v[178:181], v[96:99]
	v_mfma_f32_16x16x32_f16 v[84:87], v[202:205], v[186:189], v[84:87]
	v_mfma_f32_16x16x32_f16 v[80:83], v[210:213], v[186:189], v[80:83]
	v_mfma_f32_16x16x32_f16 v[68:71], v[202:205], v[194:197], v[68:71]
	v_mfma_f32_16x16x32_f16 v[64:67], v[210:213], v[194:197], v[64:67]
	s_barrier
	s_mov_b32 m0, s24
	s_add_u32 s74, s20, s0
	s_addc_u32 s75, s21, s1
	ds_read_b128 v[166:169], v152 offset:16384
	ds_read_b128 v[170:173], v152 offset:17408
	ds_read_b128 v[174:177], v152 offset:18432
	ds_read_b128 v[178:181], v152 offset:19456
	ds_read_b128 v[182:185], v152 offset:20480
	ds_read_b128 v[186:189], v152 offset:21504
	ds_read_b128 v[190:193], v152 offset:22528
	ds_read_b128 v[194:197], v152 offset:23552
	global_load_lds_dwordx4 v128, s[20:21]
	s_mov_b32 m0, s25
	s_nop 0
	global_load_lds_dwordx4 v132, s[20:21]
	s_barrier
	s_waitcnt lgkmcnt(0)
	v_mfma_f32_16x16x32_f16 v[60:63], v[144:147], v[166:169], v[60:63]
	v_mfma_f32_16x16x32_f16 v[56:59], v[158:161], v[166:169], v[56:59]
	v_mfma_f32_16x16x32_f16 v[44:47], v[144:147], v[174:177], v[44:47]
	v_mfma_f32_16x16x32_f16 v[40:43], v[158:161], v[174:177], v[40:43]
	v_mfma_f32_16x16x32_f16 v[28:31], v[144:147], v[182:185], v[28:31]
	v_mfma_f32_16x16x32_f16 v[24:27], v[158:161], v[182:185], v[24:27]
	v_mfma_f32_16x16x32_f16 v[12:15], v[144:147], v[190:193], v[12:15]
	v_mfma_f32_16x16x32_f16 v[8:11], v[158:161], v[190:193], v[8:11]
	v_mfma_f32_16x16x32_f16 v[60:63], v[154:157], v[170:173], v[60:63]
	v_mfma_f32_16x16x32_f16 v[56:59], v[162:165], v[170:173], v[56:59]
	v_mfma_f32_16x16x32_f16 v[44:47], v[154:157], v[178:181], v[44:47]
	v_mfma_f32_16x16x32_f16 v[40:43], v[162:165], v[178:181], v[40:43]
	v_mfma_f32_16x16x32_f16 v[28:31], v[154:157], v[186:189], v[28:31]
	v_mfma_f32_16x16x32_f16 v[24:27], v[162:165], v[186:189], v[24:27]
	v_mfma_f32_16x16x32_f16 v[12:15], v[154:157], v[194:197], v[12:15]
	v_mfma_f32_16x16x32_f16 v[8:11], v[162:165], v[194:197], v[8:11]
	s_barrier
	s_add_u32 s80, s18, 0x80000
	s_addc_u32 s81, s19, 0
	s_add_i32 s79, s69, s23
	s_mov_b32 m0, s79
	s_nop 0
	global_load_lds_dwordx4 v130, s[80:81]
	s_add_i32 m0, s79, 0x2000
	s_nop 0
	global_load_lds_dwordx4 v134, s[80:81]
	s_waitcnt vmcnt(6)
	s_barrier
	v_mfma_f32_16x16x32_f16 v[52:55], v[198:201], v[166:169], v[52:55]
	v_mfma_f32_16x16x32_f16 v[48:51], v[206:209], v[166:169], v[48:51]
	v_mfma_f32_16x16x32_f16 v[36:39], v[198:201], v[174:177], v[36:39]
	v_mfma_f32_16x16x32_f16 v[32:35], v[206:209], v[174:177], v[32:35]
	v_mfma_f32_16x16x32_f16 v[20:23], v[198:201], v[182:185], v[20:23]
	v_mfma_f32_16x16x32_f16 v[16:19], v[206:209], v[182:185], v[16:19]
	v_mfma_f32_16x16x32_f16 v[4:7], v[198:201], v[190:193], v[4:7]
	v_mfma_f32_16x16x32_f16 v[0:3], v[206:209], v[190:193], v[0:3]
	v_mfma_f32_16x16x32_f16 v[52:55], v[202:205], v[170:173], v[52:55]
	v_mfma_f32_16x16x32_f16 v[48:51], v[210:213], v[170:173], v[48:51]
	v_mfma_f32_16x16x32_f16 v[36:39], v[202:205], v[178:181], v[36:39]
	v_mfma_f32_16x16x32_f16 v[32:35], v[210:213], v[178:181], v[32:35]
	v_mfma_f32_16x16x32_f16 v[20:23], v[202:205], v[186:189], v[20:23]
	v_mfma_f32_16x16x32_f16 v[16:19], v[210:213], v[186:189], v[16:19]
	v_mfma_f32_16x16x32_f16 v[4:7], v[202:205], v[194:197], v[4:7]
	v_mfma_f32_16x16x32_f16 v[0:3], v[210:213], v[194:197], v[0:3]
	s_barrier
	s_add_i32 s79, 0, 0x18000
	v_add_u32_e32 v162, s79, v149
	ds_read_b128 v[144:147], v162
	ds_read_b128 v[154:157], v162 offset:1024
	ds_read_b128 v[158:161], v162 offset:2048
	ds_read_b128 v[162:165], v162 offset:3072
	s_add_u32 s20, s20, 0x80000
	s_addc_u32 s21, s21, 0
	s_mov_b32 m0, s26
	ds_read_b128 v[166:169], v152 offset:32768
	ds_read_b128 v[170:173], v152 offset:33792
	ds_read_b128 v[174:177], v152 offset:34816
	ds_read_b128 v[178:181], v152 offset:35840
	ds_read_b128 v[182:185], v152 offset:36864
	ds_read_b128 v[186:189], v152 offset:37888
	ds_read_b128 v[190:193], v152 offset:38912
	ds_read_b128 v[194:197], v152 offset:39936
	global_load_lds_dwordx4 v128, s[20:21]
	s_mov_b32 m0, s27
	s_nop 0
	global_load_lds_dwordx4 v132, s[20:21]
	s_waitcnt lgkmcnt(8)
	s_barrier
	s_waitcnt lgkmcnt(0)
	v_mfma_f32_16x16x32_f16 v[124:127], v[144:147], v[166:169], v[124:127]
	v_mfma_f32_16x16x32_f16 v[120:123], v[158:161], v[166:169], v[120:123]
	v_mfma_f32_16x16x32_f16 v[108:111], v[144:147], v[174:177], v[108:111]
	v_mfma_f32_16x16x32_f16 v[104:107], v[158:161], v[174:177], v[104:107]
	v_mfma_f32_16x16x32_f16 v[92:95], v[144:147], v[182:185], v[92:95]
	v_mfma_f32_16x16x32_f16 v[88:91], v[158:161], v[182:185], v[88:91]
	v_mfma_f32_16x16x32_f16 v[76:79], v[144:147], v[190:193], v[76:79]
	v_mfma_f32_16x16x32_f16 v[72:75], v[158:161], v[190:193], v[72:75]
	v_mfma_f32_16x16x32_f16 v[124:127], v[154:157], v[170:173], v[124:127]
	v_mfma_f32_16x16x32_f16 v[120:123], v[162:165], v[170:173], v[120:123]
	v_mfma_f32_16x16x32_f16 v[108:111], v[154:157], v[178:181], v[108:111]
	v_mfma_f32_16x16x32_f16 v[104:107], v[162:165], v[178:181], v[104:107]
	v_mfma_f32_16x16x32_f16 v[92:95], v[154:157], v[186:189], v[92:95]
	v_mfma_f32_16x16x32_f16 v[88:91], v[162:165], v[186:189], v[88:91]
	v_mfma_f32_16x16x32_f16 v[76:79], v[154:157], v[194:197], v[76:79]
	v_mfma_f32_16x16x32_f16 v[72:75], v[162:165], v[194:197], v[72:75]
	s_barrier
	s_add_i32 s20, 0, 0x1c000
	s_add_i32 s21, s79, s23
	v_add_u32_e32 v210, s20, v149
	s_mov_b32 m0, s21
	ds_read_b128 v[198:201], v210
	ds_read_b128 v[202:205], v210 offset:1024
	ds_read_b128 v[206:209], v210 offset:2048
	ds_read_b128 v[210:213], v210 offset:3072
	global_load_lds_dwordx4 v130, s[72:73]
	s_add_i32 m0, s21, 0x2000
	s_nop 0
	global_load_lds_dwordx4 v134, s[72:73]
	s_barrier
	s_waitcnt lgkmcnt(0)
	v_mfma_f32_16x16x32_f16 v[116:119], v[198:201], v[166:169], v[116:119]
	v_mfma_f32_16x16x32_f16 v[112:115], v[206:209], v[166:169], v[112:115]
	v_mfma_f32_16x16x32_f16 v[100:103], v[198:201], v[174:177], v[100:103]
	v_mfma_f32_16x16x32_f16 v[96:99], v[206:209], v[174:177], v[96:99]
	v_mfma_f32_16x16x32_f16 v[84:87], v[198:201], v[182:185], v[84:87]
	v_mfma_f32_16x16x32_f16 v[80:83], v[206:209], v[182:185], v[80:83]
	v_mfma_f32_16x16x32_f16 v[68:71], v[198:201], v[190:193], v[68:71]
	v_mfma_f32_16x16x32_f16 v[64:67], v[206:209], v[190:193], v[64:67]
	v_mfma_f32_16x16x32_f16 v[116:119], v[202:205], v[170:173], v[116:119]
	v_mfma_f32_16x16x32_f16 v[112:115], v[210:213], v[170:173], v[112:115]
	v_mfma_f32_16x16x32_f16 v[100:103], v[202:205], v[178:181], v[100:103]
	v_mfma_f32_16x16x32_f16 v[96:99], v[210:213], v[178:181], v[96:99]
	v_mfma_f32_16x16x32_f16 v[84:87], v[202:205], v[186:189], v[84:87]
	v_mfma_f32_16x16x32_f16 v[80:83], v[210:213], v[186:189], v[80:83]
	v_mfma_f32_16x16x32_f16 v[68:71], v[202:205], v[194:197], v[68:71]
	v_mfma_f32_16x16x32_f16 v[64:67], v[210:213], v[194:197], v[64:67]
	s_barrier
	s_mov_b32 m0, s29
	ds_read_b128 v[166:169], v152 offset:49152
	ds_read_b128 v[170:173], v152 offset:50176
	ds_read_b128 v[174:177], v152 offset:51200
	ds_read_b128 v[178:181], v152 offset:52224
	ds_read_b128 v[182:185], v152 offset:53248
	ds_read_b128 v[186:189], v152 offset:54272
	ds_read_b128 v[190:193], v152 offset:55296
	ds_read_b128 v[194:197], v152 offset:56320
	global_load_lds_dwordx4 v128, s[74:75]
	s_mov_b32 m0, s30
	s_nop 0
	global_load_lds_dwordx4 v132, s[74:75]
	s_barrier
	s_waitcnt lgkmcnt(0)
	v_mfma_f32_16x16x32_f16 v[60:63], v[144:147], v[166:169], v[60:63]
	v_mfma_f32_16x16x32_f16 v[56:59], v[158:161], v[166:169], v[56:59]
	v_mfma_f32_16x16x32_f16 v[44:47], v[144:147], v[174:177], v[44:47]
	v_mfma_f32_16x16x32_f16 v[40:43], v[158:161], v[174:177], v[40:43]
	v_mfma_f32_16x16x32_f16 v[28:31], v[144:147], v[182:185], v[28:31]
	v_mfma_f32_16x16x32_f16 v[24:27], v[158:161], v[182:185], v[24:27]
	v_mfma_f32_16x16x32_f16 v[12:15], v[144:147], v[190:193], v[12:15]
	v_mfma_f32_16x16x32_f16 v[8:11], v[158:161], v[190:193], v[8:11]
	v_mfma_f32_16x16x32_f16 v[60:63], v[154:157], v[170:173], v[60:63]
	v_mfma_f32_16x16x32_f16 v[56:59], v[162:165], v[170:173], v[56:59]
	v_mfma_f32_16x16x32_f16 v[44:47], v[154:157], v[178:181], v[44:47]
	v_mfma_f32_16x16x32_f16 v[40:43], v[162:165], v[178:181], v[40:43]
	v_mfma_f32_16x16x32_f16 v[28:31], v[154:157], v[186:189], v[28:31]
	v_mfma_f32_16x16x32_f16 v[24:27], v[162:165], v[186:189], v[24:27]
	v_mfma_f32_16x16x32_f16 v[12:15], v[154:157], v[194:197], v[12:15]
	v_mfma_f32_16x16x32_f16 v[8:11], v[162:165], v[194:197], v[8:11]
	s_barrier
	s_add_u32 s18, s18, 0x80080
	s_addc_u32 s19, s19, 0
	s_add_i32 s20, s20, s23
	s_mov_b32 m0, s20
	s_nop 0
	global_load_lds_dwordx4 v130, s[18:19]
	s_add_i32 m0, s20, 0x2000
	s_nop 0
	global_load_lds_dwordx4 v134, s[18:19]
	s_waitcnt vmcnt(6)
	s_barrier
	v_mfma_f32_16x16x32_f16 v[52:55], v[198:201], v[166:169], v[52:55]
	v_mfma_f32_16x16x32_f16 v[48:51], v[206:209], v[166:169], v[48:51]
	v_mfma_f32_16x16x32_f16 v[36:39], v[198:201], v[174:177], v[36:39]
	v_mfma_f32_16x16x32_f16 v[32:35], v[206:209], v[174:177], v[32:35]
	v_mfma_f32_16x16x32_f16 v[20:23], v[198:201], v[182:185], v[20:23]
	v_mfma_f32_16x16x32_f16 v[16:19], v[206:209], v[182:185], v[16:19]
	v_mfma_f32_16x16x32_f16 v[4:7], v[198:201], v[190:193], v[4:7]
	v_mfma_f32_16x16x32_f16 v[0:3], v[206:209], v[190:193], v[0:3]
	v_mfma_f32_16x16x32_f16 v[52:55], v[202:205], v[170:173], v[52:55]
	v_mfma_f32_16x16x32_f16 v[48:51], v[210:213], v[170:173], v[48:51]
	v_mfma_f32_16x16x32_f16 v[36:39], v[202:205], v[178:181], v[36:39]
	v_mfma_f32_16x16x32_f16 v[32:35], v[210:213], v[178:181], v[32:35]
	v_mfma_f32_16x16x32_f16 v[20:23], v[202:205], v[186:189], v[20:23]
	v_mfma_f32_16x16x32_f16 v[16:19], v[210:213], v[186:189], v[16:19]
	v_mfma_f32_16x16x32_f16 v[4:7], v[202:205], v[194:197], v[4:7]
	v_mfma_f32_16x16x32_f16 v[0:3], v[210:213], v[194:197], v[0:3]
	s_barrier
	s_add_i32 s78, s78, 2
	s_add_u32 s16, s16, 0x100
	s_addc_u32 s17, s17, 0
	s_add_u32 s76, s76, 0x100
	s_addc_u32 s77, s77, 0
	s_cmp_gt_u32 s78, 29
	s_cbranch_scc0 .LBB0_197
	s_setprio 0
	v_readlane_b32 s52, v254, 21
	v_readlane_b32 s54, v254, 23
	v_readlane_b32 s55, v254, 24
	v_lshl_add_u32 v154, s14, 8, v148
	v_lshl_or_b32 v144, s4, 8, v150
	v_mov_b64_e32 v[146:147], s[54:55]
	v_mad_i64_i32 v[146:147], s[4:5], v154, s70, v[146:147]
	v_cmp_gt_i32_e32 vcc, s71, v144
	v_ashrrev_i32_e32 v145, 31, v144
	v_readlane_b32 s53, v254, 22
	v_readlane_b32 s56, v254, 25
	v_readlane_b32 s57, v254, 26
	v_readlane_b32 s58, v254, 27
	v_readlane_b32 s59, v254, 28
	v_readlane_b32 s60, v254, 29
	v_readlane_b32 s61, v254, 30
	v_readlane_b32 s62, v254, 31
	v_readlane_b32 s63, v254, 32
	v_readlane_b32 s64, v254, 33
	v_readlane_b32 s65, v254, 34
	v_readlane_b32 s66, v254, 35
	v_readlane_b32 s67, v254, 36
	s_and_saveexec_b64 s[4:5], vcc
	s_cbranch_execz .LBB0_200
	v_cvt_pk_f16_f32 v123, v122, v123
	v_cvt_pk_f16_f32 v122, v120, v121
	v_cvt_pk_f16_f32 v121, v126, v127
	v_cvt_pk_f16_f32 v120, v124, v125
	v_lshl_add_u64 v[124:125], v[144:145], 1, v[146:147]
	global_store_dwordx4 v[124:125], v[120:123], off

.LBB0_647:
	ds_read_b128 v[80:83], v243
	ds_read_b128 v[88:91], v243 offset:1024
	ds_read_b128 v[96:99], v243 offset:2048
	ds_read_b128 v[100:103], v243 offset:3072
	s_add_u32 s18, s16, 0xfff80080
	s_addc_u32 s19, s17, -1
	s_cmp_eq_u32 s80, 28
	s_cselect_b32 s21, s9, s19
	s_cselect_b32 s20, s31, s18
	s_cselect_b32 s19, s7, s79
	s_cselect_b32 s18, s77, s78
	s_add_i32 m0, s15, 0xc000
	ds_read_b128 v[120:123], v244
	ds_read_b128 v[132:135], v244 offset:1024
	ds_read_b128 v[136:139], v244 offset:2048
	ds_read_b128 v[148:151], v244 offset:3072
	ds_read_b128 v[152:155], v244 offset:4096
	ds_read_b128 v[156:159], v244 offset:5120
	ds_read_b128 v[160:163], v244 offset:6144
	ds_read_b128 v[172:175], v244 offset:7168
	global_load_lds_dwordx4 v212, s[16:17]
	s_add_i32 m0, s15, 0xe000
	s_nop 0
	global_load_lds_dwordx4 v214, s[16:17]
	s_waitcnt lgkmcnt(8)
	s_barrier
	s_waitcnt lgkmcnt(0)
	v_mfma_f32_16x16x32_f16 v[168:171], v[80:83], v[120:123], v[168:171]
	v_mfma_f32_16x16x32_f16 v[164:167], v[96:99], v[120:123], v[164:167]
	v_mfma_f32_16x16x32_f16 v[128:131], v[80:83], v[136:139], v[128:131]
	v_mfma_f32_16x16x32_f16 v[124:127], v[96:99], v[136:139], v[124:127]
	v_mfma_f32_16x16x32_f16 v[108:111], v[80:83], v[152:155], v[108:111]
	v_mfma_f32_16x16x32_f16 v[104:107], v[96:99], v[152:155], v[104:107]
	v_mfma_f32_16x16x32_f16 v[76:79], v[80:83], v[160:163], v[76:79]
	v_mfma_f32_16x16x32_f16 v[72:75], v[96:99], v[160:163], v[72:75]
	v_mfma_f32_16x16x32_f16 v[168:171], v[88:91], v[132:135], v[168:171]
	v_mfma_f32_16x16x32_f16 v[164:167], v[100:103], v[132:135], v[164:167]
	v_mfma_f32_16x16x32_f16 v[128:131], v[88:91], v[148:151], v[128:131]
	v_mfma_f32_16x16x32_f16 v[124:127], v[100:103], v[148:151], v[124:127]
	v_mfma_f32_16x16x32_f16 v[108:111], v[88:91], v[156:159], v[108:111]
	v_mfma_f32_16x16x32_f16 v[104:107], v[100:103], v[156:159], v[104:107]
	v_mfma_f32_16x16x32_f16 v[76:79], v[88:91], v[172:175], v[76:79]
	v_mfma_f32_16x16x32_f16 v[72:75], v[100:103], v[172:175], v[72:75]
	s_barrier
	s_add_i32 s81, s71, s24
	s_add_u32 s72, s18, s4
	s_addc_u32 s73, s19, s5
	s_mov_b32 m0, s81
	ds_read_b128 v[176:179], v245
	ds_read_b128 v[180:183], v245 offset:1024
	ds_read_b128 v[184:187], v245 offset:2048
	ds_read_b128 v[188:191], v245 offset:3072
	global_load_lds_dwordx4 v206, s[18:19]
	s_add_i32 m0, s81, 0x2000
	s_nop 0
	global_load_lds_dwordx4 v210, s[18:19]
	s_barrier
	s_waitcnt lgkmcnt(0)
	v_mfma_f32_16x16x32_f16 v[144:147], v[176:179], v[120:123], v[144:147]
	v_mfma_f32_16x16x32_f16 v[116:119], v[176:179], v[136:139], v[116:119]
	v_mfma_f32_16x16x32_f16 v[112:115], v[184:187], v[136:139], v[112:115]
	v_mfma_f32_16x16x32_f16 v[92:95], v[176:179], v[152:155], v[92:95]
	v_mfma_f32_16x16x32_f16 v[84:87], v[184:187], v[152:155], v[84:87]
	v_mfma_f32_16x16x32_f16 v[68:71], v[176:179], v[160:163], v[68:71]
	v_mfma_f32_16x16x32_f16 v[64:67], v[184:187], v[160:163], v[64:67]
	v_mfma_f32_16x16x32_f16 v[144:147], v[180:183], v[132:135], v[144:147]
	v_mfma_f32_16x16x32_f16 v[120:123], v[184:187], v[120:123], v[140:143]
	v_mfma_f32_16x16x32_f16 v[116:119], v[180:183], v[148:151], v[116:119]
	v_mfma_f32_16x16x32_f16 v[112:115], v[188:191], v[148:151], v[112:115]
	v_mfma_f32_16x16x32_f16 v[92:95], v[180:183], v[156:159], v[92:95]
	v_mfma_f32_16x16x32_f16 v[84:87], v[188:191], v[156:159], v[84:87]
	v_mfma_f32_16x16x32_f16 v[68:71], v[180:183], v[172:175], v[68:71]
	v_mfma_f32_16x16x32_f16 v[64:67], v[188:191], v[172:175], v[64:67]
	v_mfma_f32_16x16x32_f16 v[120:123], v[188:191], v[132:135], v[120:123]
	s_barrier
	s_mov_b32 m0, s15
	s_add_u32 s74, s20, s4
	s_addc_u32 s75, s21, s5
	ds_read_b128 v[132:135], v244 offset:16384
	ds_read_b128 v[136:139], v244 offset:17408
	ds_read_b128 v[140:143], v244 offset:18432
	ds_read_b128 v[148:151], v244 offset:19456
	ds_read_b128 v[152:155], v244 offset:20480
	ds_read_b128 v[156:159], v244 offset:21504
	ds_read_b128 v[160:163], v244 offset:22528
	ds_read_b128 v[172:175], v244 offset:23552
	global_load_lds_dwordx4 v204, s[20:21]
	s_mov_b32 m0, s25
	s_nop 0
	global_load_lds_dwordx4 v208, s[20:21]
	s_barrier
	s_waitcnt lgkmcnt(0)
	v_mfma_f32_16x16x32_f16 v[60:63], v[80:83], v[132:135], v[60:63]
	v_mfma_f32_16x16x32_f16 v[56:59], v[96:99], v[132:135], v[56:59]
	v_mfma_f32_16x16x32_f16 v[44:47], v[80:83], v[140:143], v[44:47]
	v_mfma_f32_16x16x32_f16 v[40:43], v[96:99], v[140:143], v[40:43]
	v_mfma_f32_16x16x32_f16 v[28:31], v[80:83], v[152:155], v[28:31]
	v_mfma_f32_16x16x32_f16 v[24:27], v[96:99], v[152:155], v[24:27]
	v_mfma_f32_16x16x32_f16 v[12:15], v[80:83], v[160:163], v[12:15]
	v_mfma_f32_16x16x32_f16 v[8:11], v[96:99], v[160:163], v[8:11]
	v_mfma_f32_16x16x32_f16 v[60:63], v[88:91], v[136:139], v[60:63]
	v_mfma_f32_16x16x32_f16 v[56:59], v[100:103], v[136:139], v[56:59]
	v_mfma_f32_16x16x32_f16 v[44:47], v[88:91], v[148:151], v[44:47]
	v_mfma_f32_16x16x32_f16 v[40:43], v[100:103], v[148:151], v[40:43]
	v_mfma_f32_16x16x32_f16 v[28:31], v[88:91], v[156:159], v[28:31]
	v_mfma_f32_16x16x32_f16 v[24:27], v[100:103], v[156:159], v[24:27]
	v_mfma_f32_16x16x32_f16 v[12:15], v[88:91], v[172:175], v[12:15]
	v_mfma_f32_16x16x32_f16 v[8:11], v[100:103], v[172:175], v[8:11]
	s_barrier
	s_add_u32 s82, s18, 0x80000
	s_addc_u32 s83, s19, 0
	s_add_i32 s81, s76, s24
	s_mov_b32 m0, s81
	s_nop 0
	global_load_lds_dwordx4 v206, s[82:83]
	s_add_i32 m0, s81, 0x2000
	s_nop 0
	global_load_lds_dwordx4 v210, s[82:83]
	s_waitcnt vmcnt(6)
	s_barrier
	v_mfma_f32_16x16x32_f16 v[52:55], v[176:179], v[132:135], v[52:55]
	v_mfma_f32_16x16x32_f16 v[48:51], v[184:187], v[132:135], v[48:51]
	v_mfma_f32_16x16x32_f16 v[36:39], v[176:179], v[140:143], v[36:39]
	v_mfma_f32_16x16x32_f16 v[32:35], v[184:187], v[140:143], v[32:35]
	v_mfma_f32_16x16x32_f16 v[20:23], v[176:179], v[152:155], v[20:23]
	v_mfma_f32_16x16x32_f16 v[16:19], v[184:187], v[152:155], v[16:19]
	v_mfma_f32_16x16x32_f16 v[4:7], v[176:179], v[160:163], v[4:7]
	v_mfma_f32_16x16x32_f16 v[0:3], v[184:187], v[160:163], v[0:3]
	v_mfma_f32_16x16x32_f16 v[52:55], v[180:183], v[136:139], v[52:55]
	v_mfma_f32_16x16x32_f16 v[48:51], v[188:191], v[136:139], v[48:51]
	v_mfma_f32_16x16x32_f16 v[36:39], v[180:183], v[148:151], v[36:39]
	v_mfma_f32_16x16x32_f16 v[32:35], v[188:191], v[148:151], v[32:35]
	v_mfma_f32_16x16x32_f16 v[20:23], v[180:183], v[156:159], v[20:23]
	v_mfma_f32_16x16x32_f16 v[16:19], v[188:191], v[156:159], v[16:19]
	v_mfma_f32_16x16x32_f16 v[4:7], v[180:183], v[172:175], v[4:7]
	v_mfma_f32_16x16x32_f16 v[0:3], v[188:191], v[172:175], v[0:3]
	s_barrier
	s_add_i32 s81, 0, 0x18000
	v_add_u32_e32 v100, s81, v241
	ds_read_b128 v[80:83], v100
	ds_read_b128 v[88:91], v100 offset:1024
	ds_read_b128 v[96:99], v100 offset:2048
	ds_read_b128 v[100:103], v100 offset:3072
	s_add_u32 s20, s20, 0x80000
	s_addc_u32 s21, s21, 0
	s_mov_b32 m0, s26
	ds_read_b128 v[132:135], v244 offset:32768
	ds_read_b128 v[136:139], v244 offset:33792
	ds_read_b128 v[148:151], v244 offset:34816
	ds_read_b128 v[152:155], v244 offset:35840
	ds_read_b128 v[156:159], v244 offset:36864
	ds_read_b128 v[160:163], v244 offset:37888
	ds_read_b128 v[172:175], v244 offset:38912
	ds_read_b128 v[176:179], v244 offset:39936
	global_load_lds_dwordx4 v204, s[20:21]
	s_mov_b32 m0, s27
	s_nop 0
	global_load_lds_dwordx4 v208, s[20:21]
	s_waitcnt lgkmcnt(8)
	s_barrier
	s_waitcnt lgkmcnt(0)
	v_mfma_f32_16x16x32_f16 v[140:143], v[80:83], v[132:135], v[168:171]
	v_mfma_f32_16x16x32_f16 v[168:171], v[88:91], v[136:139], v[140:143]
	v_mfma_f32_16x16x32_f16 v[140:143], v[96:99], v[132:135], v[164:167]
	v_mfma_f32_16x16x32_f16 v[128:131], v[80:83], v[148:151], v[128:131]
	v_mfma_f32_16x16x32_f16 v[124:127], v[96:99], v[148:151], v[124:127]
	v_mfma_f32_16x16x32_f16 v[108:111], v[80:83], v[156:159], v[108:111]
	v_mfma_f32_16x16x32_f16 v[104:107], v[96:99], v[156:159], v[104:107]
	v_mfma_f32_16x16x32_f16 v[76:79], v[80:83], v[172:175], v[76:79]
	v_mfma_f32_16x16x32_f16 v[72:75], v[96:99], v[172:175], v[72:75]
	v_mfma_f32_16x16x32_f16 v[164:167], v[100:103], v[136:139], v[140:143]
	v_mfma_f32_16x16x32_f16 v[128:131], v[88:91], v[152:155], v[128:131]
	v_mfma_f32_16x16x32_f16 v[124:127], v[100:103], v[152:155], v[124:127]
	v_mfma_f32_16x16x32_f16 v[108:111], v[88:91], v[160:163], v[108:111]
	v_mfma_f32_16x16x32_f16 v[104:107], v[100:103], v[160:163], v[104:107]
	v_mfma_f32_16x16x32_f16 v[76:79], v[88:91], v[176:179], v[76:79]
	v_mfma_f32_16x16x32_f16 v[72:75], v[100:103], v[176:179], v[72:75]
	s_barrier
	s_add_i32 s20, 0, 0x1c000
	v_add_u32_e32 v140, s20, v241
	s_add_i32 s21, s81, s24
	ds_read_b128 v[180:183], v140
	ds_read_b128 v[184:187], v140 offset:1024
	ds_read_b128 v[188:191], v140 offset:2048
	ds_read_b128 v[192:195], v140 offset:3072
	s_mov_b32 m0, s21
	s_nop 0
	global_load_lds_dwordx4 v206, s[72:73]
	s_add_i32 m0, s21, 0x2000
	s_nop 0
	global_load_lds_dwordx4 v210, s[72:73]
	s_barrier
	s_waitcnt lgkmcnt(0)
	v_mfma_f32_16x16x32_f16 v[140:143], v[180:183], v[132:135], v[144:147]
	v_mfma_f32_16x16x32_f16 v[120:123], v[188:191], v[132:135], v[120:123]
	v_mfma_f32_16x16x32_f16 v[116:119], v[180:183], v[148:151], v[116:119]
	v_mfma_f32_16x16x32_f16 v[112:115], v[188:191], v[148:151], v[112:115]
	v_mfma_f32_16x16x32_f16 v[92:95], v[180:183], v[156:159], v[92:95]
	v_mfma_f32_16x16x32_f16 v[84:87], v[188:191], v[156:159], v[84:87]
	v_mfma_f32_16x16x32_f16 v[68:71], v[180:183], v[172:175], v[68:71]
	v_mfma_f32_16x16x32_f16 v[64:67], v[188:191], v[172:175], v[64:67]
	v_mfma_f32_16x16x32_f16 v[144:147], v[184:187], v[136:139], v[140:143]
	v_mfma_f32_16x16x32_f16 v[140:143], v[192:195], v[136:139], v[120:123]
	v_mfma_f32_16x16x32_f16 v[116:119], v[184:187], v[152:155], v[116:119]
	v_mfma_f32_16x16x32_f16 v[112:115], v[192:195], v[152:155], v[112:115]
	v_mfma_f32_16x16x32_f16 v[92:95], v[184:187], v[160:163], v[92:95]
	v_mfma_f32_16x16x32_f16 v[84:87], v[192:195], v[160:163], v[84:87]
	v_mfma_f32_16x16x32_f16 v[68:71], v[184:187], v[176:179], v[68:71]
	v_mfma_f32_16x16x32_f16 v[64:67], v[192:195], v[176:179], v[64:67]
	s_barrier
	s_mov_b32 m0, s35
	ds_read_b128 v[120:123], v244 offset:49152
	ds_read_b128 v[132:135], v244 offset:50176
	ds_read_b128 v[136:139], v244 offset:51200
	ds_read_b128 v[148:151], v244 offset:52224
	ds_read_b128 v[152:155], v244 offset:53248
	ds_read_b128 v[156:159], v244 offset:54272
	ds_read_b128 v[160:163], v244 offset:55296
	ds_read_b128 v[172:175], v244 offset:56320
	global_load_lds_dwordx4 v204, s[74:75]
	s_mov_b32 m0, s68
	s_nop 0
	global_load_lds_dwordx4 v208, s[74:75]
	s_barrier
	s_waitcnt lgkmcnt(0)
	v_mfma_f32_16x16x32_f16 v[60:63], v[80:83], v[120:123], v[60:63]
	v_mfma_f32_16x16x32_f16 v[56:59], v[96:99], v[120:123], v[56:59]
	v_mfma_f32_16x16x32_f16 v[44:47], v[80:83], v[136:139], v[44:47]
	v_mfma_f32_16x16x32_f16 v[40:43], v[96:99], v[136:139], v[40:43]
	v_mfma_f32_16x16x32_f16 v[28:31], v[80:83], v[152:155], v[28:31]
	v_mfma_f32_16x16x32_f16 v[24:27], v[96:99], v[152:155], v[24:27]
	v_mfma_f32_16x16x32_f16 v[12:15], v[80:83], v[160:163], v[12:15]
	v_mfma_f32_16x16x32_f16 v[8:11], v[96:99], v[160:163], v[8:11]
	v_mfma_f32_16x16x32_f16 v[60:63], v[88:91], v[132:135], v[60:63]
	v_mfma_f32_16x16x32_f16 v[56:59], v[100:103], v[132:135], v[56:59]
	v_mfma_f32_16x16x32_f16 v[44:47], v[88:91], v[148:151], v[44:47]
	v_mfma_f32_16x16x32_f16 v[40:43], v[100:103], v[148:151], v[40:43]
	v_mfma_f32_16x16x32_f16 v[28:31], v[88:91], v[156:159], v[28:31]
	v_mfma_f32_16x16x32_f16 v[24:27], v[100:103], v[156:159], v[24:27]
	v_mfma_f32_16x16x32_f16 v[12:15], v[88:91], v[172:175], v[12:15]
	v_mfma_f32_16x16x32_f16 v[8:11], v[100:103], v[172:175], v[8:11]
	s_barrier
	s_add_u32 s18, s18, 0x80080
	s_addc_u32 s19, s19, 0
	s_add_i32 s20, s20, s24
	s_mov_b32 m0, s20
	s_nop 0
	global_load_lds_dwordx4 v206, s[18:19]
	s_add_i32 m0, s20, 0x2000
	s_nop 0
	global_load_lds_dwordx4 v210, s[18:19]
	s_waitcnt vmcnt(6)
	s_barrier
	v_mfma_f32_16x16x32_f16 v[52:55], v[180:183], v[120:123], v[52:55]
	v_mfma_f32_16x16x32_f16 v[48:51], v[188:191], v[120:123], v[48:51]
	v_mfma_f32_16x16x32_f16 v[36:39], v[180:183], v[136:139], v[36:39]
	v_mfma_f32_16x16x32_f16 v[32:35], v[188:191], v[136:139], v[32:35]
	v_mfma_f32_16x16x32_f16 v[20:23], v[180:183], v[152:155], v[20:23]
	v_mfma_f32_16x16x32_f16 v[16:19], v[188:191], v[152:155], v[16:19]
	v_mfma_f32_16x16x32_f16 v[4:7], v[180:183], v[160:163], v[4:7]
	v_mfma_f32_16x16x32_f16 v[0:3], v[188:191], v[160:163], v[0:3]
	v_mfma_f32_16x16x32_f16 v[52:55], v[184:187], v[132:135], v[52:55]
	v_mfma_f32_16x16x32_f16 v[48:51], v[192:195], v[132:135], v[48:51]
	v_mfma_f32_16x16x32_f16 v[36:39], v[184:187], v[148:151], v[36:39]
	v_mfma_f32_16x16x32_f16 v[32:35], v[192:195], v[148:151], v[32:35]
	v_mfma_f32_16x16x32_f16 v[20:23], v[184:187], v[156:159], v[20:23]
	v_mfma_f32_16x16x32_f16 v[16:19], v[192:195], v[156:159], v[16:19]
	v_mfma_f32_16x16x32_f16 v[4:7], v[184:187], v[172:175], v[4:7]
	v_mfma_f32_16x16x32_f16 v[0:3], v[192:195], v[172:175], v[0:3]
	s_barrier
	s_add_i32 s80, s80, 2
	s_add_u32 s16, s16, 0x100
	s_addc_u32 s17, s17, 0
	s_add_u32 s78, s78, 0x100
	s_addc_u32 s79, s79, 0
	s_cmp_gt_u32 s80, 29
	s_cbranch_scc0 .LBB0_647
	s_setprio 0
	s_lshl_b32 s7, s14, 8
	s_add_i32 s9, s7, 0xffffe000
	s_lshr_b32 s9, s9, 11
	s_mulk_i32 s9, 0x1800
	s_addk_i32 s9, 0x1800
	s_cmp_gt_i32 s14, 31
	s_cselect_b32 s16, s9, 0
	s_ashr_i32 s17, s16, 31
	v_lshl_or_b32 v120, s30, 8, v242
	s_lshl_b64 s[16:17], s[16:17], 2
	s_add_u32 s16, s29, s16
	v_ashrrev_i32_e32 v121, 31, v120
	v_add_u32_e32 v122, s7, v240
	s_addc_u32 s17, s34, s17
	v_lshlrev_b64 v[220:221], 1, v[120:121]
	v_ashrrev_i32_e32 v123, 31, v122
	v_lshl_add_u64 v[88:89], v[120:121], 2, s[16:17]
	v_lshl_add_u64 v[120:121], s[40:41], 0, v[220:221]
	v_lshlrev_b64 v[236:237], 12, v[122:123]
	v_lshl_add_u64 v[132:133], v[120:121], 0, v[236:237]
	global_load_dwordx4 v[96:99], v[88:89], off offset:16
	global_load_dwordx4 v[100:103], v[88:89], off
	global_load_dwordx4 v[80:83], v[88:89], off offset:528
	s_nop 0
	global_load_dwordx4 v[88:91], v[88:89], off offset:512
	s_nop 0
	global_load_dwordx4 v[246:249], v[132:133], off nt
	global_load_dwordx4 v[200:203], v[132:133], off offset:256 nt
	v_or_b32_e32 v132, 16, v122
	v_ashrrev_i32_e32 v133, 31, v132
	v_lshlrev_b64 v[234:235], 12, v[132:133]
	v_lshl_add_u64 v[132:133], v[120:121], 0, v[234:235]
	global_load_dwordx4 v[196:199], v[132:133], off nt
	global_load_dwordx4 v[192:195], v[132:133], off offset:256 nt
	v_or_b32_e32 v132, 32, v122
	v_ashrrev_i32_e32 v133, 31, v132
	v_lshlrev_b64 v[232:233], 12, v[132:133]
	v_lshl_add_u64 v[132:133], v[120:121], 0, v[232:233]
	global_load_dwordx4 v[188:191], v[132:133], off nt
	global_load_dwordx4 v[184:187], v[132:133], off offset:256 nt
	v_or_b32_e32 v122, 48, v122
	v_ashrrev_i32_e32 v123, 31, v122
	v_lshlrev_b64 v[230:231], 12, v[122:123]
	v_lshl_add_u64 v[122:123], v[120:121], 0, v[230:231]
	global_load_dwordx4 v[180:183], v[122:123], off nt
	global_load_dwordx4 v[176:179], v[122:123], off offset:256 nt
	s_mov_b64 s[16:17], 0x80000
	v_lshl_add_u64 v[228:229], v[236:237], 0, s[16:17]
	v_lshl_add_u64 v[122:123], v[120:121], 0, v[228:229]
	global_load_dwordx4 v[172:175], v[122:123], off nt
	global_load_dwordx4 v[160:163], v[122:123], off offset:256 nt
	s_mov_b64 s[16:17], 0x90000
	v_lshl_add_u64 v[226:227], v[236:237], 0, s[16:17]
	v_lshl_add_u64 v[122:123], v[120:121], 0, v[226:227]
	global_load_dwordx4 v[156:159], v[122:123], off nt
	global_load_dwordx4 v[152:155], v[122:123], off offset:256 nt
	s_mov_b64 s[16:17], 0xa0000
	v_lshl_add_u64 v[224:225], v[236:237], 0, s[16:17]
	v_lshl_add_u64 v[122:123], v[120:121], 0, v[224:225]
	global_load_dwordx4 v[148:151], v[122:123], off nt
	global_load_dwordx4 v[136:139], v[122:123], off offset:256 nt
	s_mov_b64 s[16:17], 0xb0000
	v_lshl_add_u64 v[222:223], v[236:237], 0, s[16:17]
	v_lshl_add_u64 v[120:121], v[120:121], 0, v[222:223]
	global_load_dwordx4 v[132:135], v[120:121], off nt
	s_nop 0
	global_load_dwordx4 v[120:123], v[120:121], off offset:256 nt
	s_and_b64 vcc, exec, s[2:3]
	s_mov_b32 s30, s6
	s_mov_b32 s14, s8
	s_mov_b64 s[18:19], s[12:13]
	s_mov_b64 s[16:17], s[10:11]
	s_waitcnt vmcnt(0)
	v_cvt_f32_f16_e32 v250, v246
	v_cvt_f32_f16_sdwa v251, v246 dst_sel:DWORD dst_unused:UNUSED_PAD src0_sel:WORD_1
	v_pk_fma_f32 v[168:169], v[168:169], v[100:101], v[250:251]
	s_nop 0
	v_cvt_pk_f16_f32 v246, v168, v169
	v_cvt_f32_f16_e32 v168, v248
	v_cvt_f32_f16_sdwa v169, v248 dst_sel:DWORD dst_unused:UNUSED_PAD src0_sel:WORD_1
	v_pk_fma_f32 v[164:165], v[164:165], v[96:97], v[168:169]
	s_nop 0
	v_cvt_pk_f16_f32 v248, v164, v165
	v_cvt_f32_f16_e32 v164, v247
	v_cvt_f32_f16_sdwa v165, v247 dst_sel:DWORD dst_unused:UNUSED_PAD src0_sel:WORD_1
	v_pk_fma_f32 v[164:165], v[170:171], v[102:103], v[164:165]
	s_nop 0
	v_cvt_pk_f16_f32 v247, v164, v165
	v_cvt_f32_f16_e32 v164, v249
	v_cvt_f32_f16_sdwa v165, v249 dst_sel:DWORD dst_unused:UNUSED_PAD src0_sel:WORD_1
	v_pk_fma_f32 v[164:165], v[166:167], v[98:99], v[164:165]
	s_nop 0
	v_cvt_pk_f16_f32 v249, v164, v165
	v_lshl_add_u64 v[164:165], s[0:1], 0, v[236:237]
	v_lshl_add_u64 v[168:169], v[164:165], 0, v[220:221]
	v_cvt_f32_f16_e32 v164, v200
	v_cvt_f32_f16_sdwa v165, v200 dst_sel:DWORD dst_unused:UNUSED_PAD src0_sel:WORD_1
	global_store_dwordx4 v[168:169], v[246:249], off
	v_pk_fma_f32 v[144:145], v[144:145], v[88:89], v[164:165]
	s_nop 0
	v_cvt_pk_f16_f32 v164, v144, v145
	v_cvt_f32_f16_e32 v144, v202
	v_cvt_f32_f16_sdwa v145, v202 dst_sel:DWORD dst_unused:UNUSED_PAD src0_sel:WORD_1
	v_pk_fma_f32 v[140:141], v[140:141], v[80:81], v[144:145]
	s_nop 0
	v_cvt_pk_f16_f32 v166, v140, v141
	v_cvt_f32_f16_e32 v140, v201
	v_cvt_f32_f16_sdwa v141, v201 dst_sel:DWORD dst_unused:UNUSED_PAD src0_sel:WORD_1
	v_pk_fma_f32 v[140:141], v[146:147], v[90:91], v[140:141]
	s_nop 0
	v_cvt_pk_f16_f32 v165, v140, v141
	v_cvt_f32_f16_e32 v140, v203
	v_cvt_f32_f16_sdwa v141, v203 dst_sel:DWORD dst_unused:UNUSED_PAD src0_sel:WORD_1
	v_pk_fma_f32 v[140:141], v[142:143], v[82:83], v[140:141]
	s_nop 0
	v_cvt_pk_f16_f32 v167, v140, v141
	v_cvt_f32_f16_e32 v140, v196
	v_cvt_f32_f16_sdwa v141, v196 dst_sel:DWORD dst_unused:UNUSED_PAD src0_sel:WORD_1
	global_store_dwordx4 v[168:169], v[164:167], off offset:256
	v_pk_fma_f32 v[128:129], v[128:129], v[100:101], v[140:141]
	s_nop 0
	v_cvt_pk_f16_f32 v140, v128, v129
	v_cvt_f32_f16_e32 v128, v198
	v_cvt_f32_f16_sdwa v129, v198 dst_sel:DWORD dst_unused:UNUSED_PAD src0_sel:WORD_1
	v_pk_fma_f32 v[124:125], v[124:125], v[96:97], v[128:129]
	s_nop 0
	v_cvt_pk_f16_f32 v142, v124, v125
	v_cvt_f32_f16_e32 v124, v197
	v_cvt_f32_f16_sdwa v125, v197 dst_sel:DWORD dst_unused:UNUSED_PAD src0_sel:WORD_1
	v_pk_fma_f32 v[124:125], v[130:131], v[102:103], v[124:125]
	s_nop 0
	v_cvt_pk_f16_f32 v141, v124, v125
	v_cvt_f32_f16_e32 v124, v199
	v_cvt_f32_f16_sdwa v125, v199 dst_sel:DWORD dst_unused:UNUSED_PAD src0_sel:WORD_1
	v_pk_fma_f32 v[124:125], v[126:127], v[98:99], v[124:125]
	s_nop 0
	v_cvt_pk_f16_f32 v143, v124, v125
	v_lshl_add_u64 v[124:125], s[0:1], 0, v[234:235]
	v_lshl_add_u64 v[128:129], v[124:125], 0, v[220:221]
	v_cvt_f32_f16_e32 v124, v192
	v_cvt_f32_f16_sdwa v125, v192 dst_sel:DWORD dst_unused:UNUSED_PAD src0_sel:WORD_1
	global_store_dwordx4 v[128:129], v[140:143], off
	v_pk_fma_f32 v[116:117], v[116:117], v[88:89], v[124:125]
	s_nop 0
	v_cvt_pk_f16_f32 v124, v116, v117
	v_cvt_f32_f16_e32 v116, v194
	v_cvt_f32_f16_sdwa v117, v194 dst_sel:DWORD dst_unused:UNUSED_PAD src0_sel:WORD_1
	v_pk_fma_f32 v[112:113], v[112:113], v[80:81], v[116:117]
	s_nop 0
	v_cvt_pk_f16_f32 v126, v112, v113
	v_cvt_f32_f16_e32 v112, v193
	v_cvt_f32_f16_sdwa v113, v193 dst_sel:DWORD dst_unused:UNUSED_PAD src0_sel:WORD_1
	v_pk_fma_f32 v[112:113], v[118:119], v[90:91], v[112:113]
	s_nop 0
	v_cvt_pk_f16_f32 v125, v112, v113
	v_cvt_f32_f16_e32 v112, v195
	v_cvt_f32_f16_sdwa v113, v195 dst_sel:DWORD dst_unused:UNUSED_PAD src0_sel:WORD_1
	v_pk_fma_f32 v[112:113], v[114:115], v[82:83], v[112:113]
	s_nop 0
	v_cvt_pk_f16_f32 v127, v112, v113
	v_cvt_f32_f16_e32 v112, v188
	v_cvt_f32_f16_sdwa v113, v188 dst_sel:DWORD dst_unused:UNUSED_PAD src0_sel:WORD_1
	global_store_dwordx4 v[128:129], v[124:127], off offset:256
	v_pk_fma_f32 v[108:109], v[108:109], v[100:101], v[112:113]
	s_nop 0
	v_cvt_pk_f16_f32 v112, v108, v109
	v_cvt_f32_f16_e32 v108, v190
	v_cvt_f32_f16_sdwa v109, v190 dst_sel:DWORD dst_unused:UNUSED_PAD src0_sel:WORD_1
	v_pk_fma_f32 v[104:105], v[104:105], v[96:97], v[108:109]
	s_nop 0
	v_cvt_pk_f16_f32 v114, v104, v105
	v_cvt_f32_f16_e32 v104, v189
	v_cvt_f32_f16_sdwa v105, v189 dst_sel:DWORD dst_unused:UNUSED_PAD src0_sel:WORD_1
	v_pk_fma_f32 v[104:105], v[110:111], v[102:103], v[104:105]
	s_nop 0
	v_cvt_pk_f16_f32 v113, v104, v105
	v_cvt_f32_f16_e32 v104, v191
	v_cvt_f32_f16_sdwa v105, v191 dst_sel:DWORD dst_unused:UNUSED_PAD src0_sel:WORD_1
	v_pk_fma_f32 v[104:105], v[106:107], v[98:99], v[104:105]
	s_nop 0
	v_cvt_pk_f16_f32 v115, v104, v105
	v_lshl_add_u64 v[104:105], s[0:1], 0, v[232:233]
	v_lshl_add_u64 v[108:109], v[104:105], 0, v[220:221]
	v_cvt_f32_f16_e32 v104, v184
	v_cvt_f32_f16_sdwa v105, v184 dst_sel:DWORD dst_unused:UNUSED_PAD src0_sel:WORD_1
	global_store_dwordx4 v[108:109], v[112:115], off
	v_pk_fma_f32 v[92:93], v[92:93], v[88:89], v[104:105]
	s_nop 0
	v_cvt_pk_f16_f32 v104, v92, v93
	v_cvt_f32_f16_e32 v92, v186
	v_cvt_f32_f16_sdwa v93, v186 dst_sel:DWORD dst_unused:UNUSED_PAD src0_sel:WORD_1
	v_pk_fma_f32 v[84:85], v[84:85], v[80:81], v[92:93]
	s_nop 0
	v_cvt_pk_f16_f32 v106, v84, v85
	v_cvt_f32_f16_e32 v84, v185
	v_cvt_f32_f16_sdwa v85, v185 dst_sel:DWORD dst_unused:UNUSED_PAD src0_sel:WORD_1
	v_pk_fma_f32 v[84:85], v[94:95], v[90:91], v[84:85]
	s_nop 0
	v_cvt_pk_f16_f32 v105, v84, v85
	v_cvt_f32_f16_e32 v84, v187
	v_cvt_f32_f16_sdwa v85, v187 dst_sel:DWORD dst_unused:UNUSED_PAD src0_sel:WORD_1
	v_pk_fma_f32 v[84:85], v[86:87], v[82:83], v[84:85]
	s_nop 0
	v_cvt_pk_f16_f32 v107, v84, v85
	v_cvt_f32_f16_e32 v84, v180
	v_cvt_f32_f16_sdwa v85, v180 dst_sel:DWORD dst_unused:UNUSED_PAD src0_sel:WORD_1
	global_store_dwordx4 v[108:109], v[104:107], off offset:256
	v_pk_fma_f32 v[76:77], v[76:77], v[100:101], v[84:85]
	s_nop 0
	v_cvt_pk_f16_f32 v84, v76, v77
	v_cvt_f32_f16_e32 v76, v182
	v_cvt_f32_f16_sdwa v77, v182 dst_sel:DWORD dst_unused:UNUSED_PAD src0_sel:WORD_1
	v_pk_fma_f32 v[72:73], v[72:73], v[96:97], v[76:77]
	s_nop 0
	v_cvt_pk_f16_f32 v86, v72, v73
	v_cvt_f32_f16_e32 v72, v181
	v_cvt_f32_f16_sdwa v73, v181 dst_sel:DWORD dst_unused:UNUSED_PAD src0_sel:WORD_1
	v_pk_fma_f32 v[72:73], v[78:79], v[102:103], v[72:73]
	s_nop 0
	v_cvt_pk_f16_f32 v85, v72, v73
	v_cvt_f32_f16_e32 v72, v183
	v_cvt_f32_f16_sdwa v73, v183 dst_sel:DWORD dst_unused:UNUSED_PAD src0_sel:WORD_1
	v_pk_fma_f32 v[72:73], v[74:75], v[98:99], v[72:73]
	s_nop 0
	v_cvt_pk_f16_f32 v87, v72, v73
	v_lshl_add_u64 v[72:73], s[0:1], 0, v[230:231]
	v_lshl_add_u64 v[76:77], v[72:73], 0, v[220:221]
	v_cvt_f32_f16_e32 v72, v176
	v_cvt_f32_f16_sdwa v73, v176 dst_sel:DWORD dst_unused:UNUSED_PAD src0_sel:WORD_1
	global_store_dwordx4 v[76:77], v[84:87], off
	v_pk_fma_f32 v[68:69], v[68:69], v[88:89], v[72:73]
	s_nop 0
	v_cvt_pk_f16_f32 v72, v68, v69
	v_cvt_f32_f16_e32 v68, v178
	v_cvt_f32_f16_sdwa v69, v178 dst_sel:DWORD dst_unused:UNUSED_PAD src0_sel:WORD_1
	v_pk_fma_f32 v[64:65], v[64:65], v[80:81], v[68:69]
	s_nop 0
	v_cvt_pk_f16_f32 v74, v64, v65
	v_cvt_f32_f16_e32 v64, v177
	v_cvt_f32_f16_sdwa v65, v177 dst_sel:DWORD dst_unused:UNUSED_PAD src0_sel:WORD_1
	v_pk_fma_f32 v[64:65], v[70:71], v[90:91], v[64:65]
	s_nop 0
	v_cvt_pk_f16_f32 v73, v64, v65
	v_cvt_f32_f16_e32 v64, v179
	v_cvt_f32_f16_sdwa v65, v179 dst_sel:DWORD dst_unused:UNUSED_PAD src0_sel:WORD_1
	v_pk_fma_f32 v[64:65], v[66:67], v[82:83], v[64:65]
	s_nop 0
	v_cvt_pk_f16_f32 v75, v64, v65
	v_cvt_f32_f16_e32 v64, v172
	v_cvt_f32_f16_sdwa v65, v172 dst_sel:DWORD dst_unused:UNUSED_PAD src0_sel:WORD_1
	global_store_dwordx4 v[76:77], v[72:75], off offset:256
	v_pk_fma_f32 v[60:61], v[60:61], v[100:101], v[64:65]
	s_nop 0
	v_cvt_pk_f16_f32 v64, v60, v61
	v_cvt_f32_f16_e32 v60, v174
	v_cvt_f32_f16_sdwa v61, v174 dst_sel:DWORD dst_unused:UNUSED_PAD src0_sel:WORD_1
	v_pk_fma_f32 v[56:57], v[56:57], v[96:97], v[60:61]
	s_nop 0
	v_cvt_pk_f16_f32 v66, v56, v57
	v_cvt_f32_f16_e32 v56, v173
	v_cvt_f32_f16_sdwa v57, v173 dst_sel:DWORD dst_unused:UNUSED_PAD src0_sel:WORD_1
	v_pk_fma_f32 v[56:57], v[62:63], v[102:103], v[56:57]
	s_nop 0
	v_cvt_pk_f16_f32 v65, v56, v57
	v_cvt_f32_f16_e32 v56, v175
	v_cvt_f32_f16_sdwa v57, v175 dst_sel:DWORD dst_unused:UNUSED_PAD src0_sel:WORD_1
	v_pk_fma_f32 v[56:57], v[58:59], v[98:99], v[56:57]
	s_nop 0
	v_cvt_pk_f16_f32 v67, v56, v57
	v_lshl_add_u64 v[56:57], s[0:1], 0, v[228:229]
	v_lshl_add_u64 v[60:61], v[56:57], 0, v[220:221]
	v_cvt_f32_f16_e32 v56, v160
	v_cvt_f32_f16_sdwa v57, v160 dst_sel:DWORD dst_unused:UNUSED_PAD src0_sel:WORD_1
	global_store_dwordx4 v[60:61], v[64:67], off
	v_pk_fma_f32 v[52:53], v[52:53], v[88:89], v[56:57]
	s_nop 0
	v_cvt_pk_f16_f32 v56, v52, v53
	v_cvt_f32_f16_e32 v52, v162
	v_cvt_f32_f16_sdwa v53, v162 dst_sel:DWORD dst_unused:UNUSED_PAD src0_sel:WORD_1
	v_pk_fma_f32 v[48:49], v[48:49], v[80:81], v[52:53]
	s_nop 0
	v_cvt_pk_f16_f32 v58, v48, v49
	v_cvt_f32_f16_e32 v48, v161
	v_cvt_f32_f16_sdwa v49, v161 dst_sel:DWORD dst_unused:UNUSED_PAD src0_sel:WORD_1
	v_pk_fma_f32 v[48:49], v[54:55], v[90:91], v[48:49]
	s_nop 0
	v_cvt_pk_f16_f32 v57, v48, v49
	v_cvt_f32_f16_e32 v48, v163
	v_cvt_f32_f16_sdwa v49, v163 dst_sel:DWORD dst_unused:UNUSED_PAD src0_sel:WORD_1
	v_pk_fma_f32 v[48:49], v[50:51], v[82:83], v[48:49]
	s_nop 0
	v_cvt_pk_f16_f32 v59, v48, v49
	v_cvt_f32_f16_e32 v48, v156
	v_cvt_f32_f16_sdwa v49, v156 dst_sel:DWORD dst_unused:UNUSED_PAD src0_sel:WORD_1
	global_store_dwordx4 v[60:61], v[56:59], off offset:256
	v_pk_fma_f32 v[44:45], v[44:45], v[100:101], v[48:49]
	s_nop 0
	v_cvt_pk_f16_f32 v48, v44, v45
	v_cvt_f32_f16_e32 v44, v158
	v_cvt_f32_f16_sdwa v45, v158 dst_sel:DWORD dst_unused:UNUSED_PAD src0_sel:WORD_1
	v_pk_fma_f32 v[40:41], v[40:41], v[96:97], v[44:45]
	s_nop 0
	v_cvt_pk_f16_f32 v50, v40, v41
	v_cvt_f32_f16_e32 v40, v157
	v_cvt_f32_f16_sdwa v41, v157 dst_sel:DWORD dst_unused:UNUSED_PAD src0_sel:WORD_1
	v_pk_fma_f32 v[40:41], v[46:47], v[102:103], v[40:41]
	s_nop 0
	v_cvt_pk_f16_f32 v49, v40, v41
	v_cvt_f32_f16_e32 v40, v159
	v_cvt_f32_f16_sdwa v41, v159 dst_sel:DWORD dst_unused:UNUSED_PAD src0_sel:WORD_1
	v_pk_fma_f32 v[40:41], v[42:43], v[98:99], v[40:41]
	s_nop 0
	v_cvt_pk_f16_f32 v51, v40, v41
	v_lshl_add_u64 v[40:41], s[0:1], 0, v[226:227]
	v_lshl_add_u64 v[44:45], v[40:41], 0, v[220:221]
	v_cvt_f32_f16_e32 v40, v152
	v_cvt_f32_f16_sdwa v41, v152 dst_sel:DWORD dst_unused:UNUSED_PAD src0_sel:WORD_1
	global_store_dwordx4 v[44:45], v[48:51], off
	v_pk_fma_f32 v[36:37], v[36:37], v[88:89], v[40:41]
	s_nop 0
	v_cvt_pk_f16_f32 v40, v36, v37
	v_cvt_f32_f16_e32 v36, v154
	v_cvt_f32_f16_sdwa v37, v154 dst_sel:DWORD dst_unused:UNUSED_PAD src0_sel:WORD_1
	v_pk_fma_f32 v[32:33], v[32:33], v[80:81], v[36:37]
	s_nop 0
	v_cvt_pk_f16_f32 v42, v32, v33
	v_cvt_f32_f16_e32 v32, v153
	v_cvt_f32_f16_sdwa v33, v153 dst_sel:DWORD dst_unused:UNUSED_PAD src0_sel:WORD_1
	v_pk_fma_f32 v[32:33], v[38:39], v[90:91], v[32:33]
	s_nop 0
	v_cvt_pk_f16_f32 v41, v32, v33
	v_cvt_f32_f16_e32 v32, v155
	v_cvt_f32_f16_sdwa v33, v155 dst_sel:DWORD dst_unused:UNUSED_PAD src0_sel:WORD_1
	v_pk_fma_f32 v[32:33], v[34:35], v[82:83], v[32:33]
	s_nop 0
	v_cvt_pk_f16_f32 v43, v32, v33
	v_cvt_f32_f16_e32 v32, v148
	v_cvt_f32_f16_sdwa v33, v148 dst_sel:DWORD dst_unused:UNUSED_PAD src0_sel:WORD_1
	global_store_dwordx4 v[44:45], v[40:43], off offset:256
	v_pk_fma_f32 v[28:29], v[28:29], v[100:101], v[32:33]
	s_nop 0
	v_cvt_pk_f16_f32 v32, v28, v29
	v_cvt_f32_f16_e32 v28, v150
	v_cvt_f32_f16_sdwa v29, v150 dst_sel:DWORD dst_unused:UNUSED_PAD src0_sel:WORD_1
	v_pk_fma_f32 v[24:25], v[24:25], v[96:97], v[28:29]
	s_nop 0
	v_cvt_pk_f16_f32 v34, v24, v25
	v_cvt_f32_f16_e32 v24, v149
	v_cvt_f32_f16_sdwa v25, v149 dst_sel:DWORD dst_unused:UNUSED_PAD src0_sel:WORD_1
	v_pk_fma_f32 v[24:25], v[30:31], v[102:103], v[24:25]
	s_nop 0
	v_cvt_pk_f16_f32 v33, v24, v25
	v_cvt_f32_f16_e32 v24, v151
	v_cvt_f32_f16_sdwa v25, v151 dst_sel:DWORD dst_unused:UNUSED_PAD src0_sel:WORD_1
	v_pk_fma_f32 v[24:25], v[26:27], v[98:99], v[24:25]
	s_nop 0
	v_cvt_pk_f16_f32 v35, v24, v25
	v_lshl_add_u64 v[24:25], s[0:1], 0, v[224:225]
	v_lshl_add_u64 v[28:29], v[24:25], 0, v[220:221]
	v_cvt_f32_f16_e32 v24, v136
	v_cvt_f32_f16_sdwa v25, v136 dst_sel:DWORD dst_unused:UNUSED_PAD src0_sel:WORD_1
	global_store_dwordx4 v[28:29], v[32:35], off
	v_pk_fma_f32 v[20:21], v[20:21], v[88:89], v[24:25]
	s_nop 0
	v_cvt_pk_f16_f32 v24, v20, v21
	v_cvt_f32_f16_e32 v20, v138
	v_cvt_f32_f16_sdwa v21, v138 dst_sel:DWORD dst_unused:UNUSED_PAD src0_sel:WORD_1
	v_pk_fma_f32 v[16:17], v[16:17], v[80:81], v[20:21]
	s_nop 0
	v_cvt_pk_f16_f32 v26, v16, v17
	v_cvt_f32_f16_e32 v16, v137
	v_cvt_f32_f16_sdwa v17, v137 dst_sel:DWORD dst_unused:UNUSED_PAD src0_sel:WORD_1
	v_pk_fma_f32 v[16:17], v[22:23], v[90:91], v[16:17]
	s_nop 0
	v_cvt_pk_f16_f32 v25, v16, v17
	v_cvt_f32_f16_e32 v16, v139
	v_cvt_f32_f16_sdwa v17, v139 dst_sel:DWORD dst_unused:UNUSED_PAD src0_sel:WORD_1
	v_pk_fma_f32 v[16:17], v[18:19], v[82:83], v[16:17]
	s_nop 0
	v_cvt_pk_f16_f32 v27, v16, v17
	v_cvt_f32_f16_e32 v16, v132
	v_cvt_f32_f16_sdwa v17, v132 dst_sel:DWORD dst_unused:UNUSED_PAD src0_sel:WORD_1
	global_store_dwordx4 v[28:29], v[24:27], off offset:256
	v_pk_fma_f32 v[12:13], v[12:13], v[100:101], v[16:17]
	s_nop 0
	v_cvt_pk_f16_f32 v16, v12, v13
	v_cvt_f32_f16_e32 v12, v134
	v_cvt_f32_f16_sdwa v13, v134 dst_sel:DWORD dst_unused:UNUSED_PAD src0_sel:WORD_1
	v_pk_fma_f32 v[8:9], v[8:9], v[96:97], v[12:13]
	s_nop 0
	v_cvt_pk_f16_f32 v18, v8, v9
	v_cvt_f32_f16_e32 v8, v133
	v_cvt_f32_f16_sdwa v9, v133 dst_sel:DWORD dst_unused:UNUSED_PAD src0_sel:WORD_1
	v_pk_fma_f32 v[8:9], v[14:15], v[102:103], v[8:9]
	s_nop 0
	v_cvt_pk_f16_f32 v17, v8, v9
	v_cvt_f32_f16_e32 v8, v135
	v_cvt_f32_f16_sdwa v9, v135 dst_sel:DWORD dst_unused:UNUSED_PAD src0_sel:WORD_1
	v_pk_fma_f32 v[8:9], v[10:11], v[98:99], v[8:9]
	s_nop 0
	v_cvt_pk_f16_f32 v19, v8, v9
	v_lshl_add_u64 v[8:9], s[0:1], 0, v[222:223]
	v_lshl_add_u64 v[12:13], v[8:9], 0, v[220:221]
	v_cvt_f32_f16_e32 v8, v120
	v_cvt_f32_f16_sdwa v9, v120 dst_sel:DWORD dst_unused:UNUSED_PAD src0_sel:WORD_1
	global_store_dwordx4 v[12:13], v[16:19], off
	v_pk_fma_f32 v[4:5], v[4:5], v[88:89], v[8:9]
	s_nop 0
	v_cvt_pk_f16_f32 v8, v4, v5
	v_cvt_f32_f16_e32 v4, v122
	v_cvt_f32_f16_sdwa v5, v122 dst_sel:DWORD dst_unused:UNUSED_PAD src0_sel:WORD_1
	v_pk_fma_f32 v[0:1], v[0:1], v[80:81], v[4:5]
	s_nop 0
	v_cvt_pk_f16_f32 v10, v0, v1
	v_cvt_f32_f16_e32 v0, v121
	v_cvt_f32_f16_sdwa v1, v121 dst_sel:DWORD dst_unused:UNUSED_PAD src0_sel:WORD_1
	v_pk_fma_f32 v[0:1], v[6:7], v[90:91], v[0:1]
	s_nop 0
	v_cvt_pk_f16_f32 v9, v0, v1
	v_cvt_f32_f16_e32 v0, v123
	v_cvt_f32_f16_sdwa v1, v123 dst_sel:DWORD dst_unused:UNUSED_PAD src0_sel:WORD_1
	v_pk_fma_f32 v[0:1], v[2:3], v[82:83], v[0:1]
	s_nop 0
	v_cvt_pk_f16_f32 v11, v0, v1
	global_store_dwordx4 v[12:13], v[8:11], off offset:256
	s_cbranch_vccz .LBB0_640
	s_waitcnt vmcnt(0)
	s_cmpk_gt_u32 s22, 0xff
	s_cbranch_scc1 .LBB0_651
	s_barrier

.LBB0_1185:
	ds_read_b128 v[88:91], v243
	ds_read_b128 v[96:99], v243 offset:1024
	ds_read_b128 v[108:111], v243 offset:2048
	ds_read_b128 v[116:119], v243 offset:3072
	s_add_u32 s26, s24, 0xfff80080
	s_addc_u32 s27, s25, -1
	s_cmp_eq_u32 s64, 28
	s_cselect_b32 s29, s17, s27
	s_cselect_b32 s28, s31, s26
	s_cselect_b32 s27, s15, s63
	s_cselect_b32 s26, s61, s62
	s_add_i32 m0, s23, 0xc000
	ds_read_b128 v[128:131], v244
	ds_read_b128 v[136:139], v244 offset:1024
	ds_read_b128 v[144:147], v244 offset:2048
	ds_read_b128 v[148:151], v244 offset:3072
	ds_read_b128 v[152:155], v244 offset:4096
	ds_read_b128 v[164:167], v244 offset:5120
	ds_read_b128 v[168:171], v244 offset:6144
	ds_read_b128 v[172:175], v244 offset:7168
	global_load_lds_dwordx4 v212, s[24:25]
	s_add_i32 m0, s23, 0xe000
	s_nop 0
	global_load_lds_dwordx4 v214, s[24:25]
	s_waitcnt lgkmcnt(8)
	s_barrier
	s_waitcnt lgkmcnt(0)
	v_mfma_f32_16x16x32_f16 v[160:163], v[88:91], v[128:131], v[160:163]
	v_mfma_f32_16x16x32_f16 v[156:159], v[108:111], v[128:131], v[156:159]
	v_mfma_f32_16x16x32_f16 v[124:127], v[88:91], v[144:147], v[124:127]
	v_mfma_f32_16x16x32_f16 v[120:123], v[108:111], v[144:147], v[120:123]
	v_mfma_f32_16x16x32_f16 v[100:103], v[88:91], v[152:155], v[100:103]
	v_mfma_f32_16x16x32_f16 v[92:95], v[108:111], v[152:155], v[92:95]
	v_mfma_f32_16x16x32_f16 v[76:79], v[88:91], v[168:171], v[76:79]
	v_mfma_f32_16x16x32_f16 v[72:75], v[108:111], v[168:171], v[72:75]
	v_mfma_f32_16x16x32_f16 v[160:163], v[96:99], v[136:139], v[160:163]
	v_mfma_f32_16x16x32_f16 v[156:159], v[116:119], v[136:139], v[156:159]
	v_mfma_f32_16x16x32_f16 v[124:127], v[96:99], v[148:151], v[124:127]
	v_mfma_f32_16x16x32_f16 v[120:123], v[116:119], v[148:151], v[120:123]
	v_mfma_f32_16x16x32_f16 v[100:103], v[96:99], v[164:167], v[100:103]
	v_mfma_f32_16x16x32_f16 v[92:95], v[116:119], v[164:167], v[92:95]
	v_mfma_f32_16x16x32_f16 v[76:79], v[96:99], v[172:175], v[76:79]
	v_mfma_f32_16x16x32_f16 v[72:75], v[116:119], v[172:175], v[72:75]
	s_barrier
	s_add_i32 s65, s59, s44
	s_add_u32 s72, s26, s6
	s_addc_u32 s73, s27, s7
	s_mov_b32 m0, s65
	ds_read_b128 v[176:179], v245
	ds_read_b128 v[180:183], v245 offset:1024
	ds_read_b128 v[184:187], v245 offset:2048
	ds_read_b128 v[188:191], v245 offset:3072
	global_load_lds_dwordx4 v206, s[26:27]
	s_add_i32 m0, s65, 0x2000
	s_nop 0
	global_load_lds_dwordx4 v210, s[26:27]
	s_barrier
	s_waitcnt lgkmcnt(0)
	v_mfma_f32_16x16x32_f16 v[140:143], v[176:179], v[128:131], v[140:143]
	v_mfma_f32_16x16x32_f16 v[112:115], v[176:179], v[144:147], v[112:115]
	v_mfma_f32_16x16x32_f16 v[104:107], v[184:187], v[144:147], v[104:107]
	v_mfma_f32_16x16x32_f16 v[84:87], v[176:179], v[152:155], v[84:87]
	v_mfma_f32_16x16x32_f16 v[80:83], v[184:187], v[152:155], v[80:83]
	v_mfma_f32_16x16x32_f16 v[68:71], v[176:179], v[168:171], v[68:71]
	v_mfma_f32_16x16x32_f16 v[64:67], v[184:187], v[168:171], v[64:67]
	v_mfma_f32_16x16x32_f16 v[140:143], v[180:183], v[136:139], v[140:143]
	v_mfma_f32_16x16x32_f16 v[128:131], v[184:187], v[128:131], v[132:135]
	v_mfma_f32_16x16x32_f16 v[112:115], v[180:183], v[148:151], v[112:115]
	v_mfma_f32_16x16x32_f16 v[104:107], v[188:191], v[148:151], v[104:107]
	v_mfma_f32_16x16x32_f16 v[84:87], v[180:183], v[164:167], v[84:87]
	v_mfma_f32_16x16x32_f16 v[80:83], v[188:191], v[164:167], v[80:83]
	v_mfma_f32_16x16x32_f16 v[68:71], v[180:183], v[172:175], v[68:71]
	v_mfma_f32_16x16x32_f16 v[64:67], v[188:191], v[172:175], v[64:67]
	v_mfma_f32_16x16x32_f16 v[128:131], v[188:191], v[136:139], v[128:131]
	s_barrier
	s_mov_b32 m0, s23
	s_add_u32 s74, s28, s6
	s_addc_u32 s75, s29, s7
	ds_read_b128 v[132:135], v244 offset:16384
	ds_read_b128 v[136:139], v244 offset:17408
	ds_read_b128 v[144:147], v244 offset:18432
	ds_read_b128 v[148:151], v244 offset:19456
	ds_read_b128 v[152:155], v244 offset:20480
	ds_read_b128 v[164:167], v244 offset:21504
	ds_read_b128 v[168:171], v244 offset:22528
	ds_read_b128 v[172:175], v244 offset:23552
	global_load_lds_dwordx4 v204, s[28:29]
	s_mov_b32 m0, s45
	s_nop 0
	global_load_lds_dwordx4 v208, s[28:29]
	s_barrier
	s_waitcnt lgkmcnt(0)
	v_mfma_f32_16x16x32_f16 v[60:63], v[88:91], v[132:135], v[60:63]
	v_mfma_f32_16x16x32_f16 v[56:59], v[108:111], v[132:135], v[56:59]
	v_mfma_f32_16x16x32_f16 v[44:47], v[88:91], v[144:147], v[44:47]
	v_mfma_f32_16x16x32_f16 v[40:43], v[108:111], v[144:147], v[40:43]
	v_mfma_f32_16x16x32_f16 v[28:31], v[88:91], v[152:155], v[28:31]
	v_mfma_f32_16x16x32_f16 v[24:27], v[108:111], v[152:155], v[24:27]
	v_mfma_f32_16x16x32_f16 v[12:15], v[88:91], v[168:171], v[12:15]
	v_mfma_f32_16x16x32_f16 v[8:11], v[108:111], v[168:171], v[8:11]
	v_mfma_f32_16x16x32_f16 v[60:63], v[96:99], v[136:139], v[60:63]
	v_mfma_f32_16x16x32_f16 v[56:59], v[116:119], v[136:139], v[56:59]
	v_mfma_f32_16x16x32_f16 v[44:47], v[96:99], v[148:151], v[44:47]
	v_mfma_f32_16x16x32_f16 v[40:43], v[116:119], v[148:151], v[40:43]
	v_mfma_f32_16x16x32_f16 v[28:31], v[96:99], v[164:167], v[28:31]
	v_mfma_f32_16x16x32_f16 v[24:27], v[116:119], v[164:167], v[24:27]
	v_mfma_f32_16x16x32_f16 v[12:15], v[96:99], v[172:175], v[12:15]
	v_mfma_f32_16x16x32_f16 v[8:11], v[116:119], v[172:175], v[8:11]
	s_barrier
	s_add_u32 s66, s26, 0x80000
	s_addc_u32 s67, s27, 0
	s_add_i32 s65, s60, s44
	s_mov_b32 m0, s65
	s_nop 0
	global_load_lds_dwordx4 v206, s[66:67]
	s_add_i32 m0, s65, 0x2000
	s_nop 0
	global_load_lds_dwordx4 v210, s[66:67]
	s_waitcnt vmcnt(6)
	s_barrier
	v_mfma_f32_16x16x32_f16 v[52:55], v[176:179], v[132:135], v[52:55]
	v_mfma_f32_16x16x32_f16 v[48:51], v[184:187], v[132:135], v[48:51]
	v_mfma_f32_16x16x32_f16 v[36:39], v[176:179], v[144:147], v[36:39]
	v_mfma_f32_16x16x32_f16 v[32:35], v[184:187], v[144:147], v[32:35]
	v_mfma_f32_16x16x32_f16 v[20:23], v[176:179], v[152:155], v[20:23]
	v_mfma_f32_16x16x32_f16 v[16:19], v[184:187], v[152:155], v[16:19]
	v_mfma_f32_16x16x32_f16 v[4:7], v[176:179], v[168:171], v[4:7]
	v_mfma_f32_16x16x32_f16 v[0:3], v[184:187], v[168:171], v[0:3]
	v_mfma_f32_16x16x32_f16 v[52:55], v[180:183], v[136:139], v[52:55]
	v_mfma_f32_16x16x32_f16 v[48:51], v[188:191], v[136:139], v[48:51]
	v_mfma_f32_16x16x32_f16 v[36:39], v[180:183], v[148:151], v[36:39]
	v_mfma_f32_16x16x32_f16 v[32:35], v[188:191], v[148:151], v[32:35]
	v_mfma_f32_16x16x32_f16 v[20:23], v[180:183], v[164:167], v[20:23]
	v_mfma_f32_16x16x32_f16 v[16:19], v[188:191], v[164:167], v[16:19]
	v_mfma_f32_16x16x32_f16 v[4:7], v[180:183], v[172:175], v[4:7]
	v_mfma_f32_16x16x32_f16 v[0:3], v[188:191], v[172:175], v[0:3]
	s_barrier
	s_add_i32 s65, 0, 0x18000
	v_add_u32_e32 v116, s65, v241
	ds_read_b128 v[88:91], v116
	ds_read_b128 v[96:99], v116 offset:1024
	ds_read_b128 v[108:111], v116 offset:2048
	ds_read_b128 v[116:119], v116 offset:3072
	s_add_u32 s28, s28, 0x80000
	s_addc_u32 s29, s29, 0
	s_mov_b32 m0, s48
	ds_read_b128 v[132:135], v244 offset:32768
	ds_read_b128 v[136:139], v244 offset:33792
	ds_read_b128 v[144:147], v244 offset:34816
	ds_read_b128 v[148:151], v244 offset:35840
	ds_read_b128 v[152:155], v244 offset:36864
	ds_read_b128 v[164:167], v244 offset:37888
	ds_read_b128 v[168:171], v244 offset:38912
	ds_read_b128 v[172:175], v244 offset:39936
	global_load_lds_dwordx4 v204, s[28:29]
	s_mov_b32 m0, s49
	s_nop 0
	global_load_lds_dwordx4 v208, s[28:29]
	s_waitcnt lgkmcnt(8)
	s_barrier
	s_waitcnt lgkmcnt(0)
	v_mfma_f32_16x16x32_f16 v[160:163], v[88:91], v[132:135], v[160:163]
	v_mfma_f32_16x16x32_f16 v[156:159], v[108:111], v[132:135], v[156:159]
	v_mfma_f32_16x16x32_f16 v[124:127], v[88:91], v[144:147], v[124:127]
	v_mfma_f32_16x16x32_f16 v[120:123], v[108:111], v[144:147], v[120:123]
	v_mfma_f32_16x16x32_f16 v[100:103], v[88:91], v[152:155], v[100:103]
	v_mfma_f32_16x16x32_f16 v[92:95], v[108:111], v[152:155], v[92:95]
	v_mfma_f32_16x16x32_f16 v[76:79], v[88:91], v[168:171], v[76:79]
	v_mfma_f32_16x16x32_f16 v[72:75], v[108:111], v[168:171], v[72:75]
	v_mfma_f32_16x16x32_f16 v[160:163], v[96:99], v[136:139], v[160:163]
	v_mfma_f32_16x16x32_f16 v[156:159], v[116:119], v[136:139], v[156:159]
	v_mfma_f32_16x16x32_f16 v[124:127], v[96:99], v[148:151], v[124:127]
	v_mfma_f32_16x16x32_f16 v[120:123], v[116:119], v[148:151], v[120:123]
	v_mfma_f32_16x16x32_f16 v[100:103], v[96:99], v[164:167], v[100:103]
	v_mfma_f32_16x16x32_f16 v[92:95], v[116:119], v[164:167], v[92:95]
	v_mfma_f32_16x16x32_f16 v[76:79], v[96:99], v[172:175], v[76:79]
	v_mfma_f32_16x16x32_f16 v[72:75], v[116:119], v[172:175], v[72:75]
	s_barrier
	s_add_i32 s28, 0, 0x1c000
	s_add_i32 s29, s65, s44
	v_add_u32_e32 v188, s28, v241
	s_mov_b32 m0, s29
	ds_read_b128 v[176:179], v188
	ds_read_b128 v[180:183], v188 offset:1024
	ds_read_b128 v[184:187], v188 offset:2048
	ds_read_b128 v[188:191], v188 offset:3072
	global_load_lds_dwordx4 v206, s[72:73]
	s_add_i32 m0, s29, 0x2000
	s_nop 0
	global_load_lds_dwordx4 v210, s[72:73]
	s_barrier
	s_waitcnt lgkmcnt(0)
	v_mfma_f32_16x16x32_f16 v[140:143], v[176:179], v[132:135], v[140:143]
	v_mfma_f32_16x16x32_f16 v[128:131], v[184:187], v[132:135], v[128:131]
	v_mfma_f32_16x16x32_f16 v[112:115], v[176:179], v[144:147], v[112:115]
	v_mfma_f32_16x16x32_f16 v[104:107], v[184:187], v[144:147], v[104:107]
	v_mfma_f32_16x16x32_f16 v[84:87], v[176:179], v[152:155], v[84:87]
	v_mfma_f32_16x16x32_f16 v[80:83], v[184:187], v[152:155], v[80:83]
	v_mfma_f32_16x16x32_f16 v[68:71], v[176:179], v[168:171], v[68:71]
	v_mfma_f32_16x16x32_f16 v[64:67], v[184:187], v[168:171], v[64:67]
	v_mfma_f32_16x16x32_f16 v[140:143], v[180:183], v[136:139], v[140:143]
	v_mfma_f32_16x16x32_f16 v[132:135], v[188:191], v[136:139], v[128:131]
	v_mfma_f32_16x16x32_f16 v[112:115], v[180:183], v[148:151], v[112:115]
	v_mfma_f32_16x16x32_f16 v[104:107], v[188:191], v[148:151], v[104:107]
	v_mfma_f32_16x16x32_f16 v[84:87], v[180:183], v[164:167], v[84:87]
	v_mfma_f32_16x16x32_f16 v[80:83], v[188:191], v[164:167], v[80:83]
	v_mfma_f32_16x16x32_f16 v[68:71], v[180:183], v[172:175], v[68:71]
	v_mfma_f32_16x16x32_f16 v[64:67], v[188:191], v[172:175], v[64:67]
	s_barrier
	s_mov_b32 m0, s51
	ds_read_b128 v[128:131], v244 offset:49152
	ds_read_b128 v[136:139], v244 offset:50176
	ds_read_b128 v[144:147], v244 offset:51200
	ds_read_b128 v[148:151], v244 offset:52224
	ds_read_b128 v[152:155], v244 offset:53248
	ds_read_b128 v[164:167], v244 offset:54272
	ds_read_b128 v[168:171], v244 offset:55296
	ds_read_b128 v[172:175], v244 offset:56320
	global_load_lds_dwordx4 v204, s[74:75]
	s_mov_b32 m0, s54
	s_nop 0
	global_load_lds_dwordx4 v208, s[74:75]
	s_barrier
	s_waitcnt lgkmcnt(0)
	v_mfma_f32_16x16x32_f16 v[60:63], v[88:91], v[128:131], v[60:63]
	v_mfma_f32_16x16x32_f16 v[56:59], v[108:111], v[128:131], v[56:59]
	v_mfma_f32_16x16x32_f16 v[44:47], v[88:91], v[144:147], v[44:47]
	v_mfma_f32_16x16x32_f16 v[40:43], v[108:111], v[144:147], v[40:43]
	v_mfma_f32_16x16x32_f16 v[28:31], v[88:91], v[152:155], v[28:31]
	v_mfma_f32_16x16x32_f16 v[24:27], v[108:111], v[152:155], v[24:27]
	v_mfma_f32_16x16x32_f16 v[12:15], v[88:91], v[168:171], v[12:15]
	v_mfma_f32_16x16x32_f16 v[8:11], v[108:111], v[168:171], v[8:11]
	v_mfma_f32_16x16x32_f16 v[60:63], v[96:99], v[136:139], v[60:63]
	v_mfma_f32_16x16x32_f16 v[56:59], v[116:119], v[136:139], v[56:59]
	v_mfma_f32_16x16x32_f16 v[44:47], v[96:99], v[148:151], v[44:47]
	v_mfma_f32_16x16x32_f16 v[40:43], v[116:119], v[148:151], v[40:43]
	v_mfma_f32_16x16x32_f16 v[28:31], v[96:99], v[164:167], v[28:31]
	v_mfma_f32_16x16x32_f16 v[24:27], v[116:119], v[164:167], v[24:27]
	v_mfma_f32_16x16x32_f16 v[12:15], v[96:99], v[172:175], v[12:15]
	v_mfma_f32_16x16x32_f16 v[8:11], v[116:119], v[172:175], v[8:11]
	s_barrier
	s_add_u32 s26, s26, 0x80080
	s_addc_u32 s27, s27, 0
	s_add_i32 s28, s28, s44
	s_mov_b32 m0, s28
	s_nop 0
	global_load_lds_dwordx4 v206, s[26:27]
	s_add_i32 m0, s28, 0x2000
	s_nop 0
	global_load_lds_dwordx4 v210, s[26:27]
	s_waitcnt vmcnt(6)
	s_barrier
	v_mfma_f32_16x16x32_f16 v[52:55], v[176:179], v[128:131], v[52:55]
	v_mfma_f32_16x16x32_f16 v[48:51], v[184:187], v[128:131], v[48:51]
	v_mfma_f32_16x16x32_f16 v[36:39], v[176:179], v[144:147], v[36:39]
	v_mfma_f32_16x16x32_f16 v[32:35], v[184:187], v[144:147], v[32:35]
	v_mfma_f32_16x16x32_f16 v[20:23], v[176:179], v[152:155], v[20:23]
	v_mfma_f32_16x16x32_f16 v[16:19], v[184:187], v[152:155], v[16:19]
	v_mfma_f32_16x16x32_f16 v[4:7], v[176:179], v[168:171], v[4:7]
	v_mfma_f32_16x16x32_f16 v[0:3], v[184:187], v[168:171], v[0:3]
	v_mfma_f32_16x16x32_f16 v[52:55], v[180:183], v[136:139], v[52:55]
	v_mfma_f32_16x16x32_f16 v[48:51], v[188:191], v[136:139], v[48:51]
	v_mfma_f32_16x16x32_f16 v[36:39], v[180:183], v[148:151], v[36:39]
	v_mfma_f32_16x16x32_f16 v[32:35], v[188:191], v[148:151], v[32:35]
	v_mfma_f32_16x16x32_f16 v[20:23], v[180:183], v[164:167], v[20:23]
	v_mfma_f32_16x16x32_f16 v[16:19], v[188:191], v[164:167], v[16:19]
	v_mfma_f32_16x16x32_f16 v[4:7], v[180:183], v[172:175], v[4:7]
	v_mfma_f32_16x16x32_f16 v[0:3], v[188:191], v[172:175], v[0:3]
	s_barrier
	s_add_i32 s64, s64, 2
	s_add_u32 s24, s24, 0x100
	s_addc_u32 s25, s25, 0
	s_add_u32 s62, s62, 0x100
	s_addc_u32 s63, s63, 0
	s_cmp_gt_u32 s64, 29
	s_cbranch_scc0 .LBB0_1185
	s_setprio 0
	s_lshl_b32 s15, s22, 8
	s_add_i32 s17, s15, 0xffffe000
	s_lshr_b32 s17, s17, 11
	s_mulk_i32 s17, 0x1800
	s_addk_i32 s17, 0x1800
	s_cmp_gt_i32 s22, 31
	s_cselect_b32 s24, s17, 0
	s_ashr_i32 s25, s24, 31
	v_lshl_or_b32 v128, s30, 8, v242
	s_lshl_b64 s[24:25], s[24:25], 2
	s_add_u32 s24, s42, s24
	v_ashrrev_i32_e32 v129, 31, v128
	v_add_u32_e32 v130, s15, v240
	s_addc_u32 s25, s43, s25
	v_lshlrev_b64 v[220:221], 1, v[128:129]
	v_ashrrev_i32_e32 v131, 31, v130
	v_lshl_add_u64 v[96:97], v[128:129], 2, s[24:25]
	v_lshl_add_u64 v[128:129], s[4:5], 0, v[220:221]
	v_lshlrev_b64 v[236:237], 12, v[130:131]
	v_lshl_add_u64 v[136:137], v[128:129], 0, v[236:237]
	global_load_dwordx4 v[108:111], v[96:97], off offset:16
	global_load_dwordx4 v[116:119], v[96:97], off
	global_load_dwordx4 v[88:91], v[96:97], off offset:528
	s_nop 0
	global_load_dwordx4 v[96:99], v[96:97], off offset:512
	s_nop 0
	global_load_dwordx4 v[246:249], v[136:137], off nt
	global_load_dwordx4 v[200:203], v[136:137], off offset:256 nt
	v_or_b32_e32 v136, 16, v130
	v_ashrrev_i32_e32 v137, 31, v136
	v_lshlrev_b64 v[234:235], 12, v[136:137]
	v_lshl_add_u64 v[136:137], v[128:129], 0, v[234:235]
	global_load_dwordx4 v[196:199], v[136:137], off nt
	global_load_dwordx4 v[192:195], v[136:137], off offset:256 nt
	v_or_b32_e32 v136, 32, v130
	v_ashrrev_i32_e32 v137, 31, v136
	v_lshlrev_b64 v[232:233], 12, v[136:137]
	v_lshl_add_u64 v[136:137], v[128:129], 0, v[232:233]
	global_load_dwordx4 v[188:191], v[136:137], off nt
	global_load_dwordx4 v[184:187], v[136:137], off offset:256 nt
	v_readlane_b32 s64, v254, 21
	v_readlane_b32 s68, v254, 25
	v_readlane_b32 s69, v254, 26
	s_mov_b64 s[56:57], s[68:69]
	v_or_b32_e32 v130, 48, v130
	v_ashrrev_i32_e32 v131, 31, v130
	v_lshlrev_b64 v[230:231], 12, v[130:131]
	v_lshl_add_u64 v[130:131], v[128:129], 0, v[230:231]
	global_load_dwordx4 v[180:183], v[130:131], off nt
	global_load_dwordx4 v[176:179], v[130:131], off offset:256 nt
	v_lshl_add_u64 v[228:229], v[236:237], 0, s[0:1]
	v_lshl_add_u64 v[130:131], v[128:129], 0, v[228:229]
	global_load_dwordx4 v[172:175], v[130:131], off nt
	global_load_dwordx4 v[168:171], v[130:131], off offset:256 nt
	v_lshl_add_u64 v[226:227], v[236:237], 0, s[8:9]
	v_lshl_add_u64 v[130:131], v[128:129], 0, v[226:227]
	global_load_dwordx4 v[164:167], v[130:131], off nt
	global_load_dwordx4 v[152:155], v[130:131], off offset:256 nt
	v_lshl_add_u64 v[224:225], v[236:237], 0, s[10:11]
	v_lshl_add_u64 v[130:131], v[128:129], 0, v[224:225]
	global_load_dwordx4 v[148:151], v[130:131], off nt
	global_load_dwordx4 v[144:147], v[130:131], off offset:256 nt
	v_lshl_add_u64 v[222:223], v[236:237], 0, s[12:13]
	v_lshl_add_u64 v[128:129], v[128:129], 0, v[222:223]
	global_load_dwordx4 v[136:139], v[128:129], off nt
	s_nop 0
	global_load_dwordx4 v[128:131], v[128:129], off offset:256 nt
	s_and_b64 vcc, exec, s[2:3]
	s_mov_b32 s30, s14
	s_mov_b32 s22, s16
	s_mov_b64 s[26:27], s[20:21]
	s_mov_b64 s[24:25], s[18:19]
	v_readlane_b32 s65, v254, 22
	v_readlane_b32 s66, v254, 23
	v_readlane_b32 s67, v254, 24
	v_readlane_b32 s70, v254, 27
	v_readlane_b32 s71, v254, 28
	v_readlane_b32 s72, v254, 29
	v_readlane_b32 s73, v254, 30
	v_readlane_b32 s74, v254, 31
	v_readlane_b32 s75, v254, 32
	v_readlane_b32 s76, v254, 33
	v_readlane_b32 s77, v254, 34
	v_readlane_b32 s78, v254, 35
	v_readlane_b32 s79, v254, 36
	s_waitcnt vmcnt(0)
	v_cvt_f32_f16_e32 v250, v246
	v_cvt_f32_f16_sdwa v251, v246 dst_sel:DWORD dst_unused:UNUSED_PAD src0_sel:WORD_1
	v_pk_fma_f32 v[160:161], v[160:161], v[116:117], v[250:251]
	s_nop 0
	v_cvt_pk_f16_f32 v246, v160, v161
	v_cvt_f32_f16_e32 v160, v248
	v_cvt_f32_f16_sdwa v161, v248 dst_sel:DWORD dst_unused:UNUSED_PAD src0_sel:WORD_1
	v_pk_fma_f32 v[156:157], v[156:157], v[108:109], v[160:161]
	s_nop 0
	v_cvt_pk_f16_f32 v248, v156, v157
	v_cvt_f32_f16_e32 v156, v247
	v_cvt_f32_f16_sdwa v157, v247 dst_sel:DWORD dst_unused:UNUSED_PAD src0_sel:WORD_1
	v_pk_fma_f32 v[156:157], v[162:163], v[118:119], v[156:157]
	s_nop 0
	v_cvt_pk_f16_f32 v247, v156, v157
	v_cvt_f32_f16_e32 v156, v249
	v_cvt_f32_f16_sdwa v157, v249 dst_sel:DWORD dst_unused:UNUSED_PAD src0_sel:WORD_1
	v_pk_fma_f32 v[156:157], v[158:159], v[110:111], v[156:157]
	s_nop 0
	v_cvt_pk_f16_f32 v249, v156, v157
	v_lshl_add_u64 v[156:157], s[56:57], 0, v[236:237]
	v_lshl_add_u64 v[160:161], v[156:157], 0, v[220:221]
	v_cvt_f32_f16_e32 v156, v200
	v_cvt_f32_f16_sdwa v157, v200 dst_sel:DWORD dst_unused:UNUSED_PAD src0_sel:WORD_1
	global_store_dwordx4 v[160:161], v[246:249], off
	v_pk_fma_f32 v[140:141], v[140:141], v[96:97], v[156:157]
	s_nop 0
	v_cvt_pk_f16_f32 v156, v140, v141
	v_cvt_f32_f16_e32 v140, v202
	v_cvt_f32_f16_sdwa v141, v202 dst_sel:DWORD dst_unused:UNUSED_PAD src0_sel:WORD_1
	v_pk_fma_f32 v[132:133], v[132:133], v[88:89], v[140:141]
	s_nop 0
	v_cvt_pk_f16_f32 v158, v132, v133
	v_cvt_f32_f16_e32 v132, v201
	v_cvt_f32_f16_sdwa v133, v201 dst_sel:DWORD dst_unused:UNUSED_PAD src0_sel:WORD_1
	v_pk_fma_f32 v[132:133], v[142:143], v[98:99], v[132:133]
	s_nop 0
	v_cvt_pk_f16_f32 v157, v132, v133
	v_cvt_f32_f16_e32 v132, v203
	v_cvt_f32_f16_sdwa v133, v203 dst_sel:DWORD dst_unused:UNUSED_PAD src0_sel:WORD_1
	v_pk_fma_f32 v[132:133], v[134:135], v[90:91], v[132:133]
	s_nop 0
	v_cvt_pk_f16_f32 v159, v132, v133
	v_cvt_f32_f16_e32 v132, v196
	v_cvt_f32_f16_sdwa v133, v196 dst_sel:DWORD dst_unused:UNUSED_PAD src0_sel:WORD_1
	global_store_dwordx4 v[160:161], v[156:159], off offset:256
	v_pk_fma_f32 v[124:125], v[124:125], v[116:117], v[132:133]
	s_nop 0
	v_cvt_pk_f16_f32 v132, v124, v125
	v_cvt_f32_f16_e32 v124, v198
	v_cvt_f32_f16_sdwa v125, v198 dst_sel:DWORD dst_unused:UNUSED_PAD src0_sel:WORD_1
	v_pk_fma_f32 v[120:121], v[120:121], v[108:109], v[124:125]
	s_nop 0
	v_cvt_pk_f16_f32 v134, v120, v121
	v_cvt_f32_f16_e32 v120, v197
	v_cvt_f32_f16_sdwa v121, v197 dst_sel:DWORD dst_unused:UNUSED_PAD src0_sel:WORD_1
	v_pk_fma_f32 v[120:121], v[126:127], v[118:119], v[120:121]
	s_nop 0
	v_cvt_pk_f16_f32 v133, v120, v121
	v_cvt_f32_f16_e32 v120, v199
	v_cvt_f32_f16_sdwa v121, v199 dst_sel:DWORD dst_unused:UNUSED_PAD src0_sel:WORD_1
	v_pk_fma_f32 v[120:121], v[122:123], v[110:111], v[120:121]
	s_nop 0
	v_cvt_pk_f16_f32 v135, v120, v121
	v_lshl_add_u64 v[120:121], s[56:57], 0, v[234:235]
	v_lshl_add_u64 v[124:125], v[120:121], 0, v[220:221]
	v_cvt_f32_f16_e32 v120, v192
	v_cvt_f32_f16_sdwa v121, v192 dst_sel:DWORD dst_unused:UNUSED_PAD src0_sel:WORD_1
	global_store_dwordx4 v[124:125], v[132:135], off
	v_pk_fma_f32 v[112:113], v[112:113], v[96:97], v[120:121]
	s_nop 0
	v_cvt_pk_f16_f32 v120, v112, v113
	v_cvt_f32_f16_e32 v112, v194
	v_cvt_f32_f16_sdwa v113, v194 dst_sel:DWORD dst_unused:UNUSED_PAD src0_sel:WORD_1
	v_pk_fma_f32 v[104:105], v[104:105], v[88:89], v[112:113]
	s_nop 0
	v_cvt_pk_f16_f32 v122, v104, v105
	v_cvt_f32_f16_e32 v104, v193
	v_cvt_f32_f16_sdwa v105, v193 dst_sel:DWORD dst_unused:UNUSED_PAD src0_sel:WORD_1
	v_pk_fma_f32 v[104:105], v[114:115], v[98:99], v[104:105]
	s_nop 0
	v_cvt_pk_f16_f32 v121, v104, v105
	v_cvt_f32_f16_e32 v104, v195
	v_cvt_f32_f16_sdwa v105, v195 dst_sel:DWORD dst_unused:UNUSED_PAD src0_sel:WORD_1
	v_pk_fma_f32 v[104:105], v[106:107], v[90:91], v[104:105]
	s_nop 0
	v_cvt_pk_f16_f32 v123, v104, v105
	v_cvt_f32_f16_e32 v104, v188
	v_cvt_f32_f16_sdwa v105, v188 dst_sel:DWORD dst_unused:UNUSED_PAD src0_sel:WORD_1
	global_store_dwordx4 v[124:125], v[120:123], off offset:256
	v_pk_fma_f32 v[100:101], v[100:101], v[116:117], v[104:105]
	s_nop 0
	v_cvt_pk_f16_f32 v104, v100, v101
	v_cvt_f32_f16_e32 v100, v190
	v_cvt_f32_f16_sdwa v101, v190 dst_sel:DWORD dst_unused:UNUSED_PAD src0_sel:WORD_1
	v_pk_fma_f32 v[92:93], v[92:93], v[108:109], v[100:101]
	s_nop 0
	v_cvt_pk_f16_f32 v106, v92, v93
	v_cvt_f32_f16_e32 v92, v189
	v_cvt_f32_f16_sdwa v93, v189 dst_sel:DWORD dst_unused:UNUSED_PAD src0_sel:WORD_1
	v_pk_fma_f32 v[92:93], v[102:103], v[118:119], v[92:93]
	s_nop 0
	v_cvt_pk_f16_f32 v105, v92, v93
	v_cvt_f32_f16_e32 v92, v191
	v_cvt_f32_f16_sdwa v93, v191 dst_sel:DWORD dst_unused:UNUSED_PAD src0_sel:WORD_1
	v_pk_fma_f32 v[92:93], v[94:95], v[110:111], v[92:93]
	s_nop 0
	v_cvt_pk_f16_f32 v107, v92, v93
	v_lshl_add_u64 v[92:93], s[56:57], 0, v[232:233]
	v_lshl_add_u64 v[100:101], v[92:93], 0, v[220:221]
	v_cvt_f32_f16_e32 v92, v184
	v_cvt_f32_f16_sdwa v93, v184 dst_sel:DWORD dst_unused:UNUSED_PAD src0_sel:WORD_1
	global_store_dwordx4 v[100:101], v[104:107], off
	v_pk_fma_f32 v[84:85], v[84:85], v[96:97], v[92:93]
	s_nop 0
	v_cvt_pk_f16_f32 v92, v84, v85
	v_cvt_f32_f16_e32 v84, v186
	v_cvt_f32_f16_sdwa v85, v186 dst_sel:DWORD dst_unused:UNUSED_PAD src0_sel:WORD_1
	v_pk_fma_f32 v[80:81], v[80:81], v[88:89], v[84:85]
	s_nop 0
	v_cvt_pk_f16_f32 v94, v80, v81
	v_cvt_f32_f16_e32 v80, v185
	v_cvt_f32_f16_sdwa v81, v185 dst_sel:DWORD dst_unused:UNUSED_PAD src0_sel:WORD_1
	v_pk_fma_f32 v[80:81], v[86:87], v[98:99], v[80:81]
	s_nop 0
	v_cvt_pk_f16_f32 v93, v80, v81
	v_cvt_f32_f16_e32 v80, v187
	v_cvt_f32_f16_sdwa v81, v187 dst_sel:DWORD dst_unused:UNUSED_PAD src0_sel:WORD_1
	v_pk_fma_f32 v[80:81], v[82:83], v[90:91], v[80:81]
	s_nop 0
	v_cvt_pk_f16_f32 v95, v80, v81
	v_cvt_f32_f16_e32 v80, v180
	v_cvt_f32_f16_sdwa v81, v180 dst_sel:DWORD dst_unused:UNUSED_PAD src0_sel:WORD_1
	global_store_dwordx4 v[100:101], v[92:95], off offset:256
	v_pk_fma_f32 v[76:77], v[76:77], v[116:117], v[80:81]
	s_nop 0
	v_cvt_pk_f16_f32 v80, v76, v77
	v_cvt_f32_f16_e32 v76, v182
	v_cvt_f32_f16_sdwa v77, v182 dst_sel:DWORD dst_unused:UNUSED_PAD src0_sel:WORD_1
	v_pk_fma_f32 v[72:73], v[72:73], v[108:109], v[76:77]
	s_nop 0
	v_cvt_pk_f16_f32 v82, v72, v73
	v_cvt_f32_f16_e32 v72, v181
	v_cvt_f32_f16_sdwa v73, v181 dst_sel:DWORD dst_unused:UNUSED_PAD src0_sel:WORD_1
	v_pk_fma_f32 v[72:73], v[78:79], v[118:119], v[72:73]
	s_nop 0
	v_cvt_pk_f16_f32 v81, v72, v73
	v_cvt_f32_f16_e32 v72, v183
	v_cvt_f32_f16_sdwa v73, v183 dst_sel:DWORD dst_unused:UNUSED_PAD src0_sel:WORD_1
	v_pk_fma_f32 v[72:73], v[74:75], v[110:111], v[72:73]
	s_nop 0
	v_cvt_pk_f16_f32 v83, v72, v73
	v_lshl_add_u64 v[72:73], s[56:57], 0, v[230:231]
	v_lshl_add_u64 v[76:77], v[72:73], 0, v[220:221]
	v_cvt_f32_f16_e32 v72, v176
	v_cvt_f32_f16_sdwa v73, v176 dst_sel:DWORD dst_unused:UNUSED_PAD src0_sel:WORD_1
	global_store_dwordx4 v[76:77], v[80:83], off
	v_pk_fma_f32 v[68:69], v[68:69], v[96:97], v[72:73]
	s_nop 0
	v_cvt_pk_f16_f32 v72, v68, v69
	v_cvt_f32_f16_e32 v68, v178
	v_cvt_f32_f16_sdwa v69, v178 dst_sel:DWORD dst_unused:UNUSED_PAD src0_sel:WORD_1
	v_pk_fma_f32 v[64:65], v[64:65], v[88:89], v[68:69]
	s_nop 0
	v_cvt_pk_f16_f32 v74, v64, v65
	v_cvt_f32_f16_e32 v64, v177
	v_cvt_f32_f16_sdwa v65, v177 dst_sel:DWORD dst_unused:UNUSED_PAD src0_sel:WORD_1
	v_pk_fma_f32 v[64:65], v[70:71], v[98:99], v[64:65]
	s_nop 0
	v_cvt_pk_f16_f32 v73, v64, v65
	v_cvt_f32_f16_e32 v64, v179
	v_cvt_f32_f16_sdwa v65, v179 dst_sel:DWORD dst_unused:UNUSED_PAD src0_sel:WORD_1
	v_pk_fma_f32 v[64:65], v[66:67], v[90:91], v[64:65]
	s_nop 0
	v_cvt_pk_f16_f32 v75, v64, v65
	v_cvt_f32_f16_e32 v64, v172
	v_cvt_f32_f16_sdwa v65, v172 dst_sel:DWORD dst_unused:UNUSED_PAD src0_sel:WORD_1
	global_store_dwordx4 v[76:77], v[72:75], off offset:256
	v_pk_fma_f32 v[60:61], v[60:61], v[116:117], v[64:65]
	s_nop 0
	v_cvt_pk_f16_f32 v64, v60, v61
	v_cvt_f32_f16_e32 v60, v174
	v_cvt_f32_f16_sdwa v61, v174 dst_sel:DWORD dst_unused:UNUSED_PAD src0_sel:WORD_1
	v_pk_fma_f32 v[56:57], v[56:57], v[108:109], v[60:61]
	s_nop 0
	v_cvt_pk_f16_f32 v66, v56, v57
	v_cvt_f32_f16_e32 v56, v173
	v_cvt_f32_f16_sdwa v57, v173 dst_sel:DWORD dst_unused:UNUSED_PAD src0_sel:WORD_1
	v_pk_fma_f32 v[56:57], v[62:63], v[118:119], v[56:57]
	s_nop 0
	v_cvt_pk_f16_f32 v65, v56, v57
	v_cvt_f32_f16_e32 v56, v175
	v_cvt_f32_f16_sdwa v57, v175 dst_sel:DWORD dst_unused:UNUSED_PAD src0_sel:WORD_1
	v_pk_fma_f32 v[56:57], v[58:59], v[110:111], v[56:57]
	s_nop 0
	v_cvt_pk_f16_f32 v67, v56, v57
	v_lshl_add_u64 v[56:57], s[56:57], 0, v[228:229]
	v_lshl_add_u64 v[60:61], v[56:57], 0, v[220:221]
	v_cvt_f32_f16_e32 v56, v168
	v_cvt_f32_f16_sdwa v57, v168 dst_sel:DWORD dst_unused:UNUSED_PAD src0_sel:WORD_1
	global_store_dwordx4 v[60:61], v[64:67], off
	v_pk_fma_f32 v[52:53], v[52:53], v[96:97], v[56:57]
	s_nop 0
	v_cvt_pk_f16_f32 v56, v52, v53
	v_cvt_f32_f16_e32 v52, v170
	v_cvt_f32_f16_sdwa v53, v170 dst_sel:DWORD dst_unused:UNUSED_PAD src0_sel:WORD_1
	v_pk_fma_f32 v[48:49], v[48:49], v[88:89], v[52:53]
	s_nop 0
	v_cvt_pk_f16_f32 v58, v48, v49
	v_cvt_f32_f16_e32 v48, v169
	v_cvt_f32_f16_sdwa v49, v169 dst_sel:DWORD dst_unused:UNUSED_PAD src0_sel:WORD_1
	v_pk_fma_f32 v[48:49], v[54:55], v[98:99], v[48:49]
	s_nop 0
	v_cvt_pk_f16_f32 v57, v48, v49
	v_cvt_f32_f16_e32 v48, v171
	v_cvt_f32_f16_sdwa v49, v171 dst_sel:DWORD dst_unused:UNUSED_PAD src0_sel:WORD_1
	v_pk_fma_f32 v[48:49], v[50:51], v[90:91], v[48:49]
	s_nop 0
	v_cvt_pk_f16_f32 v59, v48, v49
	v_cvt_f32_f16_e32 v48, v164
	v_cvt_f32_f16_sdwa v49, v164 dst_sel:DWORD dst_unused:UNUSED_PAD src0_sel:WORD_1
	global_store_dwordx4 v[60:61], v[56:59], off offset:256
	v_pk_fma_f32 v[44:45], v[44:45], v[116:117], v[48:49]
	s_nop 0
	v_cvt_pk_f16_f32 v48, v44, v45
	v_cvt_f32_f16_e32 v44, v166
	v_cvt_f32_f16_sdwa v45, v166 dst_sel:DWORD dst_unused:UNUSED_PAD src0_sel:WORD_1
	v_pk_fma_f32 v[40:41], v[40:41], v[108:109], v[44:45]
	s_nop 0
	v_cvt_pk_f16_f32 v50, v40, v41
	v_cvt_f32_f16_e32 v40, v165
	v_cvt_f32_f16_sdwa v41, v165 dst_sel:DWORD dst_unused:UNUSED_PAD src0_sel:WORD_1
	v_pk_fma_f32 v[40:41], v[46:47], v[118:119], v[40:41]
	s_nop 0
	v_cvt_pk_f16_f32 v49, v40, v41
	v_cvt_f32_f16_e32 v40, v167
	v_cvt_f32_f16_sdwa v41, v167 dst_sel:DWORD dst_unused:UNUSED_PAD src0_sel:WORD_1
	v_pk_fma_f32 v[40:41], v[42:43], v[110:111], v[40:41]
	s_nop 0
	v_cvt_pk_f16_f32 v51, v40, v41
	v_lshl_add_u64 v[40:41], s[56:57], 0, v[226:227]
	v_lshl_add_u64 v[44:45], v[40:41], 0, v[220:221]
	v_cvt_f32_f16_e32 v40, v152
	v_cvt_f32_f16_sdwa v41, v152 dst_sel:DWORD dst_unused:UNUSED_PAD src0_sel:WORD_1
	global_store_dwordx4 v[44:45], v[48:51], off
	v_pk_fma_f32 v[36:37], v[36:37], v[96:97], v[40:41]
	s_nop 0
	v_cvt_pk_f16_f32 v40, v36, v37
	v_cvt_f32_f16_e32 v36, v154
	v_cvt_f32_f16_sdwa v37, v154 dst_sel:DWORD dst_unused:UNUSED_PAD src0_sel:WORD_1
	v_pk_fma_f32 v[32:33], v[32:33], v[88:89], v[36:37]
	s_nop 0
	v_cvt_pk_f16_f32 v42, v32, v33
	v_cvt_f32_f16_e32 v32, v153
	v_cvt_f32_f16_sdwa v33, v153 dst_sel:DWORD dst_unused:UNUSED_PAD src0_sel:WORD_1
	v_pk_fma_f32 v[32:33], v[38:39], v[98:99], v[32:33]
	s_nop 0
	v_cvt_pk_f16_f32 v41, v32, v33
	v_cvt_f32_f16_e32 v32, v155
	v_cvt_f32_f16_sdwa v33, v155 dst_sel:DWORD dst_unused:UNUSED_PAD src0_sel:WORD_1
	v_pk_fma_f32 v[32:33], v[34:35], v[90:91], v[32:33]
	s_nop 0
	v_cvt_pk_f16_f32 v43, v32, v33
	v_cvt_f32_f16_e32 v32, v148
	v_cvt_f32_f16_sdwa v33, v148 dst_sel:DWORD dst_unused:UNUSED_PAD src0_sel:WORD_1
	global_store_dwordx4 v[44:45], v[40:43], off offset:256
	v_pk_fma_f32 v[28:29], v[28:29], v[116:117], v[32:33]
	s_nop 0
	v_cvt_pk_f16_f32 v32, v28, v29
	v_cvt_f32_f16_e32 v28, v150
	v_cvt_f32_f16_sdwa v29, v150 dst_sel:DWORD dst_unused:UNUSED_PAD src0_sel:WORD_1
	v_pk_fma_f32 v[24:25], v[24:25], v[108:109], v[28:29]
	s_nop 0
	v_cvt_pk_f16_f32 v34, v24, v25
	v_cvt_f32_f16_e32 v24, v149
	v_cvt_f32_f16_sdwa v25, v149 dst_sel:DWORD dst_unused:UNUSED_PAD src0_sel:WORD_1
	v_pk_fma_f32 v[24:25], v[30:31], v[118:119], v[24:25]
	s_nop 0
	v_cvt_pk_f16_f32 v33, v24, v25
	v_cvt_f32_f16_e32 v24, v151
	v_cvt_f32_f16_sdwa v25, v151 dst_sel:DWORD dst_unused:UNUSED_PAD src0_sel:WORD_1
	v_pk_fma_f32 v[24:25], v[26:27], v[110:111], v[24:25]
	s_nop 0
	v_cvt_pk_f16_f32 v35, v24, v25
	v_lshl_add_u64 v[24:25], s[56:57], 0, v[224:225]
	v_lshl_add_u64 v[28:29], v[24:25], 0, v[220:221]
	v_cvt_f32_f16_e32 v24, v144
	v_cvt_f32_f16_sdwa v25, v144 dst_sel:DWORD dst_unused:UNUSED_PAD src0_sel:WORD_1
	global_store_dwordx4 v[28:29], v[32:35], off
	v_pk_fma_f32 v[20:21], v[20:21], v[96:97], v[24:25]
	s_nop 0
	v_cvt_pk_f16_f32 v24, v20, v21
	v_cvt_f32_f16_e32 v20, v146
	v_cvt_f32_f16_sdwa v21, v146 dst_sel:DWORD dst_unused:UNUSED_PAD src0_sel:WORD_1
	v_pk_fma_f32 v[16:17], v[16:17], v[88:89], v[20:21]
	s_nop 0
	v_cvt_pk_f16_f32 v26, v16, v17
	v_cvt_f32_f16_e32 v16, v145
	v_cvt_f32_f16_sdwa v17, v145 dst_sel:DWORD dst_unused:UNUSED_PAD src0_sel:WORD_1
	v_pk_fma_f32 v[16:17], v[22:23], v[98:99], v[16:17]
	s_nop 0
	v_cvt_pk_f16_f32 v25, v16, v17
	v_cvt_f32_f16_e32 v16, v147
	v_cvt_f32_f16_sdwa v17, v147 dst_sel:DWORD dst_unused:UNUSED_PAD src0_sel:WORD_1
	v_pk_fma_f32 v[16:17], v[18:19], v[90:91], v[16:17]
	s_nop 0
	v_cvt_pk_f16_f32 v27, v16, v17
	v_cvt_f32_f16_e32 v16, v136
	v_cvt_f32_f16_sdwa v17, v136 dst_sel:DWORD dst_unused:UNUSED_PAD src0_sel:WORD_1
	global_store_dwordx4 v[28:29], v[24:27], off offset:256
	v_pk_fma_f32 v[12:13], v[12:13], v[116:117], v[16:17]
	s_nop 0
	v_cvt_pk_f16_f32 v16, v12, v13
	v_cvt_f32_f16_e32 v12, v138
	v_cvt_f32_f16_sdwa v13, v138 dst_sel:DWORD dst_unused:UNUSED_PAD src0_sel:WORD_1
	v_pk_fma_f32 v[8:9], v[8:9], v[108:109], v[12:13]
	s_nop 0
	v_cvt_pk_f16_f32 v18, v8, v9
	v_cvt_f32_f16_e32 v8, v137
	v_cvt_f32_f16_sdwa v9, v137 dst_sel:DWORD dst_unused:UNUSED_PAD src0_sel:WORD_1
	v_pk_fma_f32 v[8:9], v[14:15], v[118:119], v[8:9]
	s_nop 0
	v_cvt_pk_f16_f32 v17, v8, v9
	v_cvt_f32_f16_e32 v8, v139
	v_cvt_f32_f16_sdwa v9, v139 dst_sel:DWORD dst_unused:UNUSED_PAD src0_sel:WORD_1
	v_pk_fma_f32 v[8:9], v[10:11], v[110:111], v[8:9]
	s_nop 0
	v_cvt_pk_f16_f32 v19, v8, v9
	v_lshl_add_u64 v[8:9], s[56:57], 0, v[222:223]
	v_lshl_add_u64 v[12:13], v[8:9], 0, v[220:221]
	v_cvt_f32_f16_e32 v8, v128
	v_cvt_f32_f16_sdwa v9, v128 dst_sel:DWORD dst_unused:UNUSED_PAD src0_sel:WORD_1
	global_store_dwordx4 v[12:13], v[16:19], off
	v_pk_fma_f32 v[4:5], v[4:5], v[96:97], v[8:9]
	s_nop 0
	v_cvt_pk_f16_f32 v8, v4, v5
	v_cvt_f32_f16_e32 v4, v130
	v_cvt_f32_f16_sdwa v5, v130 dst_sel:DWORD dst_unused:UNUSED_PAD src0_sel:WORD_1
	v_pk_fma_f32 v[0:1], v[0:1], v[88:89], v[4:5]
	s_nop 0
	v_cvt_pk_f16_f32 v10, v0, v1
	v_cvt_f32_f16_e32 v0, v129
	v_cvt_f32_f16_sdwa v1, v129 dst_sel:DWORD dst_unused:UNUSED_PAD src0_sel:WORD_1
	v_pk_fma_f32 v[0:1], v[6:7], v[98:99], v[0:1]
	s_nop 0
	v_cvt_pk_f16_f32 v9, v0, v1
	v_cvt_f32_f16_e32 v0, v131
	v_cvt_f32_f16_sdwa v1, v131 dst_sel:DWORD dst_unused:UNUSED_PAD src0_sel:WORD_1
	v_pk_fma_f32 v[0:1], v[2:3], v[90:91], v[0:1]
	s_nop 0
	v_cvt_pk_f16_f32 v11, v0, v1
	global_store_dwordx4 v[12:13], v[8:11], off offset:256
	s_cbranch_vccz .LBB0_1178
	s_waitcnt vmcnt(0)
	s_cmpk_gt_u32 s34, 0xff
	s_cbranch_scc1 .LBB0_1189
	s_barrier
